# v5 + removed the redundant s_setprio 0/1 pair in the middle of each 32-MFMA segment of the GEMM loops
# baseline (speedup 1.0000x reference)
; #define PG8_STAGE(bufoff, gbase, voff) do { _Pragma("unroll") for (int _i = 0; _i < 2; ++_i) \
;         { unsigned vo_ = (voff) + _i * voff##_d; asm volatile("" : "+v"(vo_)); __builtin_amdgcn_global_load_lds((const unsigned*)((const char*)(gbase) + vo_), (PG8_LAS unsigned*)(lds + (bufoff) + ldsw + _i * 8192), 16, 0, 0); } } while (0)
; #define PG8_LDA(dst, b, h) do { _Pragma("unroll") for (int m = 0; m < 4; ++m) _Pragma("unroll") for (int k = 0; k < 2; ++k) dst[m][k] = *(const PG8_LAS bf16x8*)(lds + PG8_SA(b, h) + aoff + m * 2048 + k * 1024); } while (0)
; #define PG8_LDB(dst, b, h) do { _Pragma("unroll") for (int n = 0; n < 2; ++n) _Pragma("unroll") for (int k = 0; k < 2; ++k) dst[n][k] = *(const PG8_LAS bf16x8*)(lds + PG8_SB(b, h) + boff + n * 2048 + k * 1024); } while (0)
; template <class Epi, class Sched, bool ALIGN_EPI, bool F8 = false>
; __device__ __forceinline__ void gemm_phase(PG8_LAS unsigned char* lds, const Gemm g, const Sched& S, const Epi& E, const int wid) {
;     ...
;         for (int t = 0; t < nt; t += 2) {
;             const bool last = (t == nt - 2);
;             const char* a1 = cA + (size_t)(t + 1) * kstep;
;             const char* a2 = last ? nA : cA + (size_t)(t + 2) * kstep; const char* b2 = last ? nB : cB + (size_t)(t + 2) * kstep;
;             const char* a3 = a2 + kstep; const char* b3 = b2 + kstep;
;             PG8_LDB(B0, 0, 0); PG8_LDB(B1, 0, 1); PG8_SCHED; PG8_LDA(At, 0, 0); PG8_STAGE(PG8_SA(1, 1), a1 + hA, voffA);
;             PG8_WAIT_V(8); PG8_WAIT_L(0); PG8_BAR; PG8_MMA(0, 0, At, B0); PG8_MMA(0, 1, At, B1); PG8_BAR; PG8_SCHED;
;             PG8_LDA(At, 0, 1); PG8_STAGE(PG8_SB(0, 0), b2, voffB); PG8_STAGE(PG8_SB(0, 1), b2 + hB, voffB); PG8_STAGE(PG8_SA(0, 0), a2, voffA);
;             PG8_WAIT_V(8); PG8_WAIT_L(0); PG8_BAR; PG8_MMA(1, 0, At, B0); PG8_MMA(1, 1, At, B1); PG8_BAR; PG8_SCHED;
;             PG8_LDB(B0, 1, 0); PG8_LDB(B1, 1, 1); PG8_SCHED; PG8_LDA(At, 1, 0); PG8_STAGE(PG8_SA(0, 1), a2 + hA, voffA);
;             PG8_WAIT_V(8); PG8_WAIT_L(0); PG8_BAR; PG8_MMA(0, 0, At, B0); PG8_MMA(0, 1, At, B1); PG8_BAR; PG8_SCHED;
;             PG8_LDA(At, 1, 1); PG8_STAGE(PG8_SB(1, 0), b3, voffB); PG8_STAGE(PG8_SB(1, 1), b3 + hB, voffB); PG8_STAGE(PG8_SA(1, 0), a3, voffA);
;             PG8_WAIT_V(8); PG8_WAIT_L(0); PG8_BAR; PG8_MMA(1, 0, At, B0); PG8_MMA(1, 1, At, B1); PG8_BAR; PG8_SCHED;
;         }
.LBB0_140:
	s_add_i32 s57, s28, 2
	s_add_u32 s30, s26, 0xfffc0080
	s_addc_u32 s29, s27, -1
	s_add_i32 s58, 0, 0x10000
	s_cmp_eq_u32 s49, s28
	s_cselect_b32 s29, s13, s29
	s_cselect_b32 s28, s15, s30
	s_cselect_b32 s31, s53, s56
	s_cselect_b32 s30, s54, s55
	s_add_i32 s60, 0, 0x14000
	v_add_u32_e32 v146, s58, v132
	v_add_u32_e32 v162, s60, v132
	ds_read_b128 v[134:137], v146
	ds_read_b128 v[138:141], v146 offset:1024
	ds_read_b128 v[142:145], v146 offset:2048
	ds_read_b128 v[146:149], v146 offset:3072
	ds_read_b128 v[150:153], v162
	ds_read_b128 v[154:157], v162 offset:1024
	ds_read_b128 v[158:161], v162 offset:2048
	ds_read_b128 v[162:165], v162 offset:3072
	ds_read_b128 v[166:169], v133
	ds_read_b128 v[170:173], v133 offset:1024
	ds_read_b128 v[174:177], v133 offset:2048
	ds_read_b128 v[178:181], v133 offset:3072
	ds_read_b128 v[182:185], v133 offset:4096
	ds_read_b128 v[186:189], v133 offset:5120
	ds_read_b128 v[190:193], v133 offset:6144
	ds_read_b128 v[194:197], v133 offset:7168
	s_add_i32 m0, s25, 0xc000
	s_nop 0
	global_load_lds_dwordx4 v128, s[26:27]
	s_add_i32 m0, s25, 0xe000
	s_nop 0
	global_load_lds_dwordx4 v131, s[26:27]
	s_waitcnt vmcnt(8)
	s_waitcnt lgkmcnt(0)
	s_barrier
	s_setprio 1
	s_waitcnt lgkmcnt(0)
	v_mfma_f32_16x16x128_f8f6f4 v[124:127], v[134:141], v[166:173], v[124:127]
	v_mfma_f32_16x16x128_f8f6f4 v[120:123], v[142:149], v[166:173], v[120:123]
	v_mfma_f32_16x16x128_f8f6f4 v[108:111], v[134:141], v[174:181], v[108:111]
	v_mfma_f32_16x16x128_f8f6f4 v[104:107], v[142:149], v[174:181], v[104:107]
	v_mfma_f32_16x16x128_f8f6f4 v[206:209], v[134:141], v[182:189], v[92:95]
	v_mfma_f32_16x16x128_f8f6f4 v[210:213], v[142:149], v[182:189], v[88:91]
	v_mfma_f32_16x16x128_f8f6f4 v[214:217], v[134:141], v[190:197], v[76:79]
	v_mfma_f32_16x16x128_f8f6f4 v[218:221], v[142:149], v[190:197], v[72:75]
	v_mfma_f32_16x16x128_f8f6f4 v[116:119], v[150:157], v[166:173], v[116:119]
	v_mfma_f32_16x16x128_f8f6f4 v[112:115], v[158:165], v[166:173], v[112:115]
	v_mfma_f32_16x16x128_f8f6f4 v[100:103], v[150:157], v[174:181], v[100:103]
	v_mfma_f32_16x16x128_f8f6f4 v[96:99], v[158:165], v[174:181], v[96:99]
	v_mfma_f32_16x16x128_f8f6f4 v[166:169], v[150:157], v[182:189], v[84:87]
	v_mfma_f32_16x16x128_f8f6f4 v[170:173], v[158:165], v[182:189], v[80:83]
	v_mfma_f32_16x16x128_f8f6f4 v[174:177], v[150:157], v[190:197], v[68:71]
	v_mfma_f32_16x16x128_f8f6f4 v[178:181], v[158:165], v[190:197], v[64:67]
	s_setprio 0
	s_barrier
	s_add_i32 s58, s58, s39
	s_nop 2
	ds_read_b128 v[64:67], v133 offset:16384
	ds_read_b128 v[68:71], v133 offset:17408
	ds_read_b128 v[72:75], v133 offset:18432
	ds_read_b128 v[76:79], v133 offset:19456
	ds_read_b128 v[80:83], v133 offset:20480
	ds_read_b128 v[84:87], v133 offset:21504
	ds_read_b128 v[88:91], v133 offset:22528
	ds_read_b128 v[92:95], v133 offset:23552
	s_mov_b32 m0, s58
	s_nop 0
	global_load_lds_dwordx4 v129, s[30:31]
	s_add_i32 m0, s58, 0x2000
	s_add_u32 s58, s30, 0x40000
	global_load_lds_dwordx4 v130, s[30:31]
	s_addc_u32 s59, s31, 0
	s_add_i32 s60, s60, s39
	s_mov_b32 m0, s60
	s_nop 0
	global_load_lds_dwordx4 v129, s[58:59]
	s_add_i32 m0, s60, 0x2000
	s_nop 0
	global_load_lds_dwordx4 v130, s[58:59]
	s_mov_b32 m0, s25
	s_nop 0
	global_load_lds_dwordx4 v128, s[28:29]
	s_mov_b32 m0, s41
	s_nop 0
	global_load_lds_dwordx4 v131, s[28:29]
	s_waitcnt vmcnt(8)
	s_waitcnt lgkmcnt(0)
	s_barrier
	s_setprio 1
	s_waitcnt lgkmcnt(0)
	v_mfma_f32_16x16x128_f8f6f4 v[60:63], v[134:141], v[64:71], v[60:63]
	v_mfma_f32_16x16x128_f8f6f4 v[56:59], v[142:149], v[64:71], v[56:59]
	v_mfma_f32_16x16x128_f8f6f4 v[182:185], v[134:141], v[72:79], v[44:47]
	v_mfma_f32_16x16x128_f8f6f4 v[186:189], v[142:149], v[72:79], v[40:43]
	v_mfma_f32_16x16x128_f8f6f4 v[190:193], v[134:141], v[80:87], v[28:31]
	v_mfma_f32_16x16x128_f8f6f4 v[194:197], v[142:149], v[80:87], v[24:27]
	v_mfma_f32_16x16x128_f8f6f4 v[242:245], v[134:141], v[88:95], v[12:15]
	v_mfma_f32_16x16x128_f8f6f4 v[246:249], v[142:149], v[88:95], v[8:11]
	v_mfma_f32_16x16x128_f8f6f4 v[52:55], v[150:157], v[64:71], v[52:55]
	v_mfma_f32_16x16x128_f8f6f4 v[48:51], v[158:165], v[64:71], v[48:51]
	v_mfma_f32_16x16x128_f8f6f4 v[250:253], v[150:157], v[72:79], v[36:39]
	v_mfma_f32_16x16x128_f8f6f4 v[228:231], v[158:165], v[72:79], v[32:35]
	v_mfma_f32_16x16x128_f8f6f4 v[202:205], v[150:157], v[80:87], v[20:23]
	v_mfma_f32_16x16x128_f8f6f4 v[236:239], v[158:165], v[80:87], v[16:19]
	v_mfma_f32_16x16x128_f8f6f4 v[224:227], v[150:157], v[88:95], v[4:7]
	v_mfma_f32_16x16x128_f8f6f4 v[232:235], v[158:165], v[88:95], v[0:3]
	s_setprio 0
	s_barrier
; #define PG8_STAGE(bufoff, gbase, voff) do { _Pragma("unroll") for (int _i = 0; _i < 2; ++_i) \
;         { unsigned vo_ = (voff) + _i * voff##_d; asm volatile("" : "+v"(vo_)); __builtin_amdgcn_global_load_lds((const unsigned*)((const char*)(gbase) + vo_), (PG8_LAS unsigned*)(lds + (bufoff) + ldsw + _i * 8192), 16, 0, 0); } } while (0)
; #define PG8_LDA(dst, b, h) do { _Pragma("unroll") for (int m = 0; m < 4; ++m) _Pragma("unroll") for (int k = 0; k < 2; ++k) dst[m][k] = *(const PG8_LAS bf16x8*)(lds + PG8_SA(b, h) + aoff + m * 2048 + k * 1024); } while (0)
; #define PG8_LDB(dst, b, h) do { _Pragma("unroll") for (int n = 0; n < 2; ++n) _Pragma("unroll") for (int k = 0; k < 2; ++k) dst[n][k] = *(const PG8_LAS bf16x8*)(lds + PG8_SB(b, h) + boff + n * 2048 + k * 1024); } while (0)
; template <class Epi, class Sched, bool ALIGN_EPI, bool F8 = false>
; __device__ __forceinline__ void gemm_phase(PG8_LAS unsigned char* lds, const Gemm g, const Sched& S, const Epi& E, const int wid) {
;     ...
;         for (int t = 0; t < nt; t += 2) {
;             const bool last = (t == nt - 2);
;             const char* a1 = cA + (size_t)(t + 1) * kstep;
;             const char* a2 = last ? nA : cA + (size_t)(t + 2) * kstep; const char* b2 = last ? nB : cB + (size_t)(t + 2) * kstep;
;             const char* a3 = a2 + kstep; const char* b3 = b2 + kstep;
;             PG8_LDB(B0, 0, 0); PG8_LDB(B1, 0, 1); PG8_SCHED; PG8_LDA(At, 0, 0); PG8_STAGE(PG8_SA(1, 1), a1 + hA, voffA);
;             PG8_WAIT_V(8); PG8_WAIT_L(0); PG8_BAR; PG8_MMA(0, 0, At, B0); PG8_MMA(0, 1, At, B1); PG8_BAR; PG8_SCHED;
;             PG8_LDA(At, 0, 1); PG8_STAGE(PG8_SB(0, 0), b2, voffB); PG8_STAGE(PG8_SB(0, 1), b2 + hB, voffB); PG8_STAGE(PG8_SA(0, 0), a2, voffA);
;             PG8_WAIT_V(8); PG8_WAIT_L(0); PG8_BAR; PG8_MMA(1, 0, At, B0); PG8_MMA(1, 1, At, B1); PG8_BAR; PG8_SCHED;
;             PG8_LDB(B0, 1, 0); PG8_LDB(B1, 1, 1); PG8_SCHED; PG8_LDA(At, 1, 0); PG8_STAGE(PG8_SA(0, 1), a2 + hA, voffA);
;             PG8_WAIT_V(8); PG8_WAIT_L(0); PG8_BAR; PG8_MMA(0, 0, At, B0); PG8_MMA(0, 1, At, B1); PG8_BAR; PG8_SCHED;
;             PG8_LDA(At, 1, 1); PG8_STAGE(PG8_SB(1, 0), b3, voffB); PG8_STAGE(PG8_SB(1, 1), b3 + hB, voffB); PG8_STAGE(PG8_SA(1, 0), a3, voffA);
;             PG8_WAIT_V(8); PG8_WAIT_L(0); PG8_BAR; PG8_MMA(1, 0, At, B0); PG8_MMA(1, 1, At, B1); PG8_BAR; PG8_SCHED;
;         }
	s_add_i32 s60, 0, 0x18000
	v_add_u32_e32 v8, s60, v132
	s_add_i32 s61, 0, 0x1c000
	s_nop 1
	ds_read_b128 v[0:3], v8
	ds_read_b128 v[4:7], v8 offset:1024
	ds_read_b128 v[16:19], v8 offset:2048
	ds_read_b128 v[20:23], v8 offset:3072
	v_add_u32_e32 v8, s61, v132
	ds_read_b128 v[134:137], v8
	ds_read_b128 v[138:141], v8 offset:1024
	ds_read_b128 v[142:145], v8 offset:2048
	ds_read_b128 v[146:149], v8 offset:3072
	s_add_u32 s58, s28, 0x40000
	s_mov_b32 m0, s42
	ds_read_b128 v[8:11], v133 offset:32768
	ds_read_b128 v[12:15], v133 offset:33792
	ds_read_b128 v[24:27], v133 offset:34816
	ds_read_b128 v[28:31], v133 offset:35840
	ds_read_b128 v[32:35], v133 offset:36864
	ds_read_b128 v[36:39], v133 offset:37888
	ds_read_b128 v[40:43], v133 offset:38912
	ds_read_b128 v[44:47], v133 offset:39936
	s_addc_u32 s59, s29, 0
	s_nop 0
	global_load_lds_dwordx4 v128, s[58:59]
	s_mov_b32 m0, s43
	s_nop 0
	global_load_lds_dwordx4 v131, s[58:59]
	s_waitcnt vmcnt(8)
	s_waitcnt lgkmcnt(0)
	s_barrier
	s_setprio 1
	s_waitcnt lgkmcnt(0)
	v_mfma_f32_16x16x128_f8f6f4 v[124:127], v[0:7], v[8:15], v[124:127]
	v_mfma_f32_16x16x128_f8f6f4 v[120:123], v[16:23], v[8:15], v[120:123]
	v_mfma_f32_16x16x128_f8f6f4 v[108:111], v[0:7], v[24:31], v[108:111]
	v_mfma_f32_16x16x128_f8f6f4 v[104:107], v[16:23], v[24:31], v[104:107]
	v_mfma_f32_16x16x128_f8f6f4 v[92:95], v[0:7], v[32:39], v[206:209]
	v_mfma_f32_16x16x128_f8f6f4 v[88:91], v[16:23], v[32:39], v[210:213]
	v_mfma_f32_16x16x128_f8f6f4 v[76:79], v[0:7], v[40:47], v[214:217]
	v_mfma_f32_16x16x128_f8f6f4 v[72:75], v[16:23], v[40:47], v[218:221]
	v_mfma_f32_16x16x128_f8f6f4 v[116:119], v[134:141], v[8:15], v[116:119]
	v_mfma_f32_16x16x128_f8f6f4 v[112:115], v[142:149], v[8:15], v[112:115]
	v_mfma_f32_16x16x128_f8f6f4 v[100:103], v[134:141], v[24:31], v[100:103]
	v_mfma_f32_16x16x128_f8f6f4 v[96:99], v[142:149], v[24:31], v[96:99]
	v_mfma_f32_16x16x128_f8f6f4 v[84:87], v[134:141], v[32:39], v[166:169]
	v_mfma_f32_16x16x128_f8f6f4 v[80:83], v[142:149], v[32:39], v[170:173]
	v_mfma_f32_16x16x128_f8f6f4 v[68:71], v[134:141], v[40:47], v[174:177]
	v_mfma_f32_16x16x128_f8f6f4 v[64:67], v[142:149], v[40:47], v[178:181]
	s_setprio 0
	s_barrier
	ds_read_b128 v[32:35], v133 offset:49152
	ds_read_b128 v[36:39], v133 offset:50176
	ds_read_b128 v[150:153], v133 offset:51200
	ds_read_b128 v[154:157], v133 offset:52224
	ds_read_b128 v[158:161], v133 offset:53248
	ds_read_b128 v[162:165], v133 offset:54272
	ds_read_b128 v[166:169], v133 offset:55296
	ds_read_b128 v[170:173], v133 offset:56320
	s_add_i32 s58, s60, s39
	s_add_u32 s100, s30, s2
	s_addc_u32 s101, s31, s3
	s_mov_b32 m0, s58
	s_nop 0
	global_load_lds_dwordx4 v129, s[100:101]
	s_add_i32 m0, s58, 0x2000
	s_add_u32 s100, s30, s2
	s_addc_u32 s101, s31, s3
	s_add_u32 s30, s30, 0x40080
	global_load_lds_dwordx4 v130, s[100:101]
	s_addc_u32 s31, s31, 0
	s_add_i32 s58, s61, s39
	s_mov_b32 m0, s58
	s_nop 0
	global_load_lds_dwordx4 v129, s[30:31]
	s_add_i32 m0, s58, 0x2000
	s_nop 0
	global_load_lds_dwordx4 v130, s[30:31]
	s_mov_b32 m0, s47
	s_add_u32 s100, s28, s2
	s_addc_u32 s101, s29, s3
	global_load_lds_dwordx4 v128, s[100:101]
	s_mov_b32 m0, s48
	s_add_u32 s100, s28, s2
	s_addc_u32 s101, s29, s3
	global_load_lds_dwordx4 v131, s[100:101]
	s_waitcnt vmcnt(8)
	s_waitcnt lgkmcnt(0)
	s_barrier
	s_setprio 1
	s_waitcnt lgkmcnt(0)
	v_mfma_f32_16x16x128_f8f6f4 v[60:63], v[0:7], v[32:39], v[60:63]
	v_mfma_f32_16x16x128_f8f6f4 v[56:59], v[16:23], v[32:39], v[56:59]
	v_mfma_f32_16x16x128_f8f6f4 v[44:47], v[0:7], v[150:157], v[182:185]
	v_mfma_f32_16x16x128_f8f6f4 v[40:43], v[16:23], v[150:157], v[186:189]
	v_mfma_f32_16x16x128_f8f6f4 v[28:31], v[0:7], v[158:165], v[190:193]
	v_mfma_f32_16x16x128_f8f6f4 v[24:27], v[16:23], v[158:165], v[194:197]
	v_mfma_f32_16x16x128_f8f6f4 v[12:15], v[0:7], v[166:173], v[242:245]
	v_mfma_f32_16x16x128_f8f6f4 v[8:11], v[16:23], v[166:173], v[246:249]
	v_mfma_f32_16x16x128_f8f6f4 v[52:55], v[134:141], v[32:39], v[52:55]
	v_mfma_f32_16x16x128_f8f6f4 v[48:51], v[142:149], v[32:39], v[48:51]
	v_mfma_f32_16x16x128_f8f6f4 v[36:39], v[134:141], v[150:157], v[250:253]
	v_mfma_f32_16x16x128_f8f6f4 v[32:35], v[142:149], v[150:157], v[228:231]
	v_mfma_f32_16x16x128_f8f6f4 v[20:23], v[134:141], v[158:165], v[202:205]
	v_mfma_f32_16x16x128_f8f6f4 v[16:19], v[142:149], v[158:165], v[236:239]
	v_mfma_f32_16x16x128_f8f6f4 v[4:7], v[134:141], v[166:173], v[224:227]
	v_mfma_f32_16x16x128_f8f6f4 v[0:3], v[142:149], v[166:173], v[232:235]
	s_setprio 0
	s_barrier
	s_add_u32 s26, s26, 0x100
	s_addc_u32 s27, s27, 0
	s_add_u32 s55, s55, 0x100
	s_addc_u32 s56, s56, 0
	s_cmp_ge_i32 s57, s44
	s_mov_b32 s28, s57
	s_cbranch_scc0 .LBB0_140
	v_mov_b32_e32 v232, v199
	v_mov_b32_e32 v233, v223
	v_mov_b32_e32 v223, 0x260
	v_mov_b32_e32 v234, 0x1e000
	v_mov_b32_e32 v235, 0x7f800000
	v_mov_b32_e32 v236, 0x7fc00000
	v_mov_b32_e32 v237, 0x7fffff
	v_mov_b64_e32 v[238:239], 0x140
	v_mov_b64_e32 v[252:253], 0x13f

; #define PG8_STAGE(bufoff, gbase, voff) do { _Pragma("unroll") for (int _i = 0; _i < 2; ++_i) \
;         { unsigned vo_ = (voff) + _i * voff##_d; asm volatile("" : "+v"(vo_)); __builtin_amdgcn_global_load_lds((const unsigned*)((const char*)(gbase) + vo_), (PG8_LAS unsigned*)(lds + (bufoff) + ldsw + _i * 8192), 16, 0, 0); } } while (0)
; #define PG8_LDA(dst, b, h) do { _Pragma("unroll") for (int m = 0; m < 4; ++m) _Pragma("unroll") for (int k = 0; k < 2; ++k) dst[m][k] = *(const PG8_LAS bf16x8*)(lds + PG8_SA(b, h) + aoff + m * 2048 + k * 1024); } while (0)
; #define PG8_LDB(dst, b, h) do { _Pragma("unroll") for (int n = 0; n < 2; ++n) _Pragma("unroll") for (int k = 0; k < 2; ++k) dst[n][k] = *(const PG8_LAS bf16x8*)(lds + PG8_SB(b, h) + boff + n * 2048 + k * 1024); } while (0)
; template <class Epi, class Sched, bool ALIGN_EPI, bool F8 = false>
; __device__ __forceinline__ void gemm_phase(PG8_LAS unsigned char* lds, const Gemm g, const Sched& S, const Epi& E, const int wid) {
;     ...
;         for (int t = 0; t < nt; t += 2) {
;             const bool last = (t == nt - 2);
;             const char* a1 = cA + (size_t)(t + 1) * kstep;
;             const char* a2 = last ? nA : cA + (size_t)(t + 2) * kstep; const char* b2 = last ? nB : cB + (size_t)(t + 2) * kstep;
;             const char* a3 = a2 + kstep; const char* b3 = b2 + kstep;
;             PG8_LDB(B0, 0, 0); PG8_LDB(B1, 0, 1); PG8_SCHED; PG8_LDA(At, 0, 0); PG8_STAGE(PG8_SA(1, 1), a1 + hA, voffA);
;             PG8_WAIT_V(8); PG8_WAIT_L(0); PG8_BAR; PG8_MMA(0, 0, At, B0); PG8_MMA(0, 1, At, B1); PG8_BAR; PG8_SCHED;
;             PG8_LDA(At, 0, 1); PG8_STAGE(PG8_SB(0, 0), b2, voffB); PG8_STAGE(PG8_SB(0, 1), b2 + hB, voffB); PG8_STAGE(PG8_SA(0, 0), a2, voffA);
;             PG8_WAIT_V(8); PG8_WAIT_L(0); PG8_BAR; PG8_MMA(1, 0, At, B0); PG8_MMA(1, 1, At, B1); PG8_BAR; PG8_SCHED;
;             PG8_LDB(B0, 1, 0); PG8_LDB(B1, 1, 1); PG8_SCHED; PG8_LDA(At, 1, 0); PG8_STAGE(PG8_SA(0, 1), a2 + hA, voffA);
;             PG8_WAIT_V(8); PG8_WAIT_L(0); PG8_BAR; PG8_MMA(0, 0, At, B0); PG8_MMA(0, 1, At, B1); PG8_BAR; PG8_SCHED;
;             PG8_LDA(At, 1, 1); PG8_STAGE(PG8_SB(1, 0), b3, voffB); PG8_STAGE(PG8_SB(1, 1), b3 + hB, voffB); PG8_STAGE(PG8_SA(1, 0), a3, voffA);
;             PG8_WAIT_V(8); PG8_WAIT_L(0); PG8_BAR; PG8_MMA(1, 0, At, B0); PG8_MMA(1, 1, At, B1); PG8_BAR; PG8_SCHED;
;         }
.LBB0_160:
	s_add_i32 s59, s10, 2
	s_add_u32 s8, s6, 0xfff80080
	s_addc_u32 s9, s7, -1
	s_add_i32 s61, 0, 0x10000
	s_cmp_eq_u32 s89, s10
	s_cselect_b32 s9, s1, s9
	s_cselect_b32 s8, s12, s8
	s_cselect_b32 s11, s13, s33
	s_cselect_b32 s10, s14, s15
	s_add_i32 s94, 0, 0x14000
	v_add_u32_e32 v140, s61, v219
	v_add_u32_e32 v156, s94, v219
	ds_read_b128 v[128:131], v140
	ds_read_b128 v[132:135], v140 offset:1024
	ds_read_b128 v[136:139], v140 offset:2048
	ds_read_b128 v[140:143], v140 offset:3072
	ds_read_b128 v[144:147], v156
	ds_read_b128 v[148:151], v156 offset:1024
	ds_read_b128 v[152:155], v156 offset:2048
	ds_read_b128 v[156:159], v156 offset:3072
	ds_read_b128 v[160:163], v220
	ds_read_b128 v[164:167], v220 offset:1024
	ds_read_b128 v[168:171], v220 offset:2048
	ds_read_b128 v[172:175], v220 offset:3072
	ds_read_b128 v[176:179], v220 offset:4096
	ds_read_b128 v[180:183], v220 offset:5120
	ds_read_b128 v[184:187], v220 offset:6144
	ds_read_b128 v[188:191], v220 offset:7168
	s_add_i32 m0, s80, 0xc000
	s_nop 0
	global_load_lds_dwordx4 v217, s[6:7]
	s_add_i32 m0, s80, 0xe000
	s_nop 0
	global_load_lds_dwordx4 v218, s[6:7]
	s_waitcnt vmcnt(8)
	s_waitcnt lgkmcnt(0)
	s_barrier
	s_setprio 1
	s_waitcnt lgkmcnt(0)
	v_mfma_f32_16x16x32_bf16 v[124:127], v[128:131], v[160:163], v[124:127]
	v_mfma_f32_16x16x32_bf16 v[116:119], v[136:139], v[160:163], v[116:119]
	v_mfma_f32_16x16x32_bf16 v[108:111], v[128:131], v[168:171], v[108:111]
	v_mfma_f32_16x16x32_bf16 v[104:107], v[136:139], v[168:171], v[104:107]
	v_mfma_f32_16x16x32_bf16 v[92:95], v[128:131], v[176:179], v[92:95]
	v_mfma_f32_16x16x32_bf16 v[88:91], v[136:139], v[176:179], v[88:91]
	v_mfma_f32_16x16x32_bf16 v[76:79], v[128:131], v[184:187], v[76:79]
	v_mfma_f32_16x16x32_bf16 v[72:75], v[136:139], v[184:187], v[72:75]
	v_mfma_f32_16x16x32_bf16 v[124:127], v[132:135], v[164:167], v[124:127]
	v_mfma_f32_16x16x32_bf16 v[116:119], v[140:143], v[164:167], v[116:119]
	v_mfma_f32_16x16x32_bf16 v[108:111], v[132:135], v[172:175], v[108:111]
	v_mfma_f32_16x16x32_bf16 v[104:107], v[140:143], v[172:175], v[104:107]
	v_mfma_f32_16x16x32_bf16 v[92:95], v[132:135], v[180:183], v[92:95]
	v_mfma_f32_16x16x32_bf16 v[88:91], v[140:143], v[180:183], v[88:91]
	v_mfma_f32_16x16x32_bf16 v[76:79], v[132:135], v[188:191], v[76:79]
	v_mfma_f32_16x16x32_bf16 v[72:75], v[140:143], v[188:191], v[72:75]
	v_mfma_f32_16x16x32_bf16 v[120:123], v[144:147], v[160:163], v[120:123]
	v_mfma_f32_16x16x32_bf16 v[112:115], v[152:155], v[160:163], v[112:115]
	v_mfma_f32_16x16x32_bf16 v[100:103], v[144:147], v[168:171], v[100:103]
	v_mfma_f32_16x16x32_bf16 v[96:99], v[152:155], v[168:171], v[96:99]
	v_mfma_f32_16x16x32_bf16 v[84:87], v[144:147], v[176:179], v[84:87]
	v_mfma_f32_16x16x32_bf16 v[80:83], v[152:155], v[176:179], v[80:83]
	v_mfma_f32_16x16x32_bf16 v[68:71], v[144:147], v[184:187], v[68:71]
	v_mfma_f32_16x16x32_bf16 v[64:67], v[152:155], v[184:187], v[64:67]
	v_mfma_f32_16x16x32_bf16 v[120:123], v[148:151], v[164:167], v[120:123]
	v_mfma_f32_16x16x32_bf16 v[112:115], v[156:159], v[164:167], v[112:115]
	v_mfma_f32_16x16x32_bf16 v[100:103], v[148:151], v[172:175], v[100:103]
	v_mfma_f32_16x16x32_bf16 v[96:99], v[156:159], v[172:175], v[96:99]
	v_mfma_f32_16x16x32_bf16 v[84:87], v[148:151], v[180:183], v[84:87]
	v_mfma_f32_16x16x32_bf16 v[80:83], v[156:159], v[180:183], v[80:83]
	v_mfma_f32_16x16x32_bf16 v[68:71], v[148:151], v[188:191], v[68:71]
	v_mfma_f32_16x16x32_bf16 v[64:67], v[156:159], v[188:191], v[64:67]
	s_setprio 0
	s_barrier
	s_add_i32 s61, s61, s79
	ds_read_b128 v[160:163], v220 offset:16384
	ds_read_b128 v[164:167], v220 offset:17408
	ds_read_b128 v[168:171], v220 offset:18432
	ds_read_b128 v[172:175], v220 offset:19456
	ds_read_b128 v[176:179], v220 offset:20480
	ds_read_b128 v[180:183], v220 offset:21504
	ds_read_b128 v[184:187], v220 offset:22528
	ds_read_b128 v[188:191], v220 offset:23552
	s_mov_b32 m0, s61
	s_nop 0
	global_load_lds_dwordx4 v217, s[10:11]
	s_add_i32 m0, s61, 0x2000
	s_add_u32 s70, s10, 0x80000
	global_load_lds_dwordx4 v218, s[10:11]
	s_addc_u32 s71, s11, 0
	s_add_i32 s61, s94, s79
	s_mov_b32 m0, s61
	s_nop 0
	global_load_lds_dwordx4 v217, s[70:71]
	s_add_i32 m0, s61, 0x2000
	s_nop 0
	global_load_lds_dwordx4 v218, s[70:71]
	s_mov_b32 m0, s80
	s_nop 0
	global_load_lds_dwordx4 v217, s[8:9]
	s_mov_b32 m0, s81
	s_nop 0
	global_load_lds_dwordx4 v218, s[8:9]
	s_waitcnt vmcnt(8)
	s_waitcnt lgkmcnt(0)
	s_barrier
	s_setprio 1
	s_waitcnt lgkmcnt(0)
	v_mfma_f32_16x16x32_bf16 v[60:63], v[128:131], v[160:163], v[60:63]
	v_mfma_f32_16x16x32_bf16 v[56:59], v[136:139], v[160:163], v[56:59]
	v_mfma_f32_16x16x32_bf16 v[44:47], v[128:131], v[168:171], v[44:47]
	v_mfma_f32_16x16x32_bf16 v[40:43], v[136:139], v[168:171], v[40:43]
	v_mfma_f32_16x16x32_bf16 v[28:31], v[128:131], v[176:179], v[28:31]
	v_mfma_f32_16x16x32_bf16 v[24:27], v[136:139], v[176:179], v[24:27]
	v_mfma_f32_16x16x32_bf16 v[12:15], v[128:131], v[184:187], v[12:15]
	v_mfma_f32_16x16x32_bf16 v[8:11], v[136:139], v[184:187], v[8:11]
	v_mfma_f32_16x16x32_bf16 v[60:63], v[132:135], v[164:167], v[60:63]
	v_mfma_f32_16x16x32_bf16 v[56:59], v[140:143], v[164:167], v[56:59]
	v_mfma_f32_16x16x32_bf16 v[44:47], v[132:135], v[172:175], v[44:47]
	v_mfma_f32_16x16x32_bf16 v[40:43], v[140:143], v[172:175], v[40:43]
	v_mfma_f32_16x16x32_bf16 v[28:31], v[132:135], v[180:183], v[28:31]
	v_mfma_f32_16x16x32_bf16 v[24:27], v[140:143], v[180:183], v[24:27]
	v_mfma_f32_16x16x32_bf16 v[12:15], v[132:135], v[188:191], v[12:15]
	v_mfma_f32_16x16x32_bf16 v[8:11], v[140:143], v[188:191], v[8:11]
	v_mfma_f32_16x16x32_bf16 v[52:55], v[144:147], v[160:163], v[52:55]
	v_mfma_f32_16x16x32_bf16 v[48:51], v[152:155], v[160:163], v[48:51]
	v_mfma_f32_16x16x32_bf16 v[36:39], v[144:147], v[168:171], v[36:39]
	v_mfma_f32_16x16x32_bf16 v[32:35], v[152:155], v[168:171], v[32:35]
	v_mfma_f32_16x16x32_bf16 v[20:23], v[144:147], v[176:179], v[20:23]
	v_mfma_f32_16x16x32_bf16 v[16:19], v[152:155], v[176:179], v[16:19]
	v_mfma_f32_16x16x32_bf16 v[4:7], v[144:147], v[184:187], v[4:7]
	v_mfma_f32_16x16x32_bf16 v[0:3], v[152:155], v[184:187], v[0:3]
	v_mfma_f32_16x16x32_bf16 v[52:55], v[148:151], v[164:167], v[52:55]
	v_mfma_f32_16x16x32_bf16 v[48:51], v[156:159], v[164:167], v[48:51]
	v_mfma_f32_16x16x32_bf16 v[36:39], v[148:151], v[172:175], v[36:39]
	v_mfma_f32_16x16x32_bf16 v[32:35], v[156:159], v[172:175], v[32:35]
	v_mfma_f32_16x16x32_bf16 v[20:23], v[148:151], v[180:183], v[20:23]
	v_mfma_f32_16x16x32_bf16 v[16:19], v[156:159], v[180:183], v[16:19]
	v_mfma_f32_16x16x32_bf16 v[4:7], v[148:151], v[188:191], v[4:7]
	v_mfma_f32_16x16x32_bf16 v[0:3], v[156:159], v[188:191], v[0:3]
	s_setprio 0
	s_barrier
; #define PG8_STAGE(bufoff, gbase, voff) do { _Pragma("unroll") for (int _i = 0; _i < 2; ++_i) \
;         { unsigned vo_ = (voff) + _i * voff##_d; asm volatile("" : "+v"(vo_)); __builtin_amdgcn_global_load_lds((const unsigned*)((const char*)(gbase) + vo_), (PG8_LAS unsigned*)(lds + (bufoff) + ldsw + _i * 8192), 16, 0, 0); } } while (0)
; #define PG8_LDA(dst, b, h) do { _Pragma("unroll") for (int m = 0; m < 4; ++m) _Pragma("unroll") for (int k = 0; k < 2; ++k) dst[m][k] = *(const PG8_LAS bf16x8*)(lds + PG8_SA(b, h) + aoff + m * 2048 + k * 1024); } while (0)
; #define PG8_LDB(dst, b, h) do { _Pragma("unroll") for (int n = 0; n < 2; ++n) _Pragma("unroll") for (int k = 0; k < 2; ++k) dst[n][k] = *(const PG8_LAS bf16x8*)(lds + PG8_SB(b, h) + boff + n * 2048 + k * 1024); } while (0)
; template <class Epi, class Sched, bool ALIGN_EPI, bool F8 = false>
; __device__ __forceinline__ void gemm_phase(PG8_LAS unsigned char* lds, const Gemm g, const Sched& S, const Epi& E, const int wid) {
;     ...
;         for (int t = 0; t < nt; t += 2) {
;             const bool last = (t == nt - 2);
;             const char* a1 = cA + (size_t)(t + 1) * kstep;
;             const char* a2 = last ? nA : cA + (size_t)(t + 2) * kstep; const char* b2 = last ? nB : cB + (size_t)(t + 2) * kstep;
;             const char* a3 = a2 + kstep; const char* b3 = b2 + kstep;
;             PG8_LDB(B0, 0, 0); PG8_LDB(B1, 0, 1); PG8_SCHED; PG8_LDA(At, 0, 0); PG8_STAGE(PG8_SA(1, 1), a1 + hA, voffA);
;             PG8_WAIT_V(8); PG8_WAIT_L(0); PG8_BAR; PG8_MMA(0, 0, At, B0); PG8_MMA(0, 1, At, B1); PG8_BAR; PG8_SCHED;
;             PG8_LDA(At, 0, 1); PG8_STAGE(PG8_SB(0, 0), b2, voffB); PG8_STAGE(PG8_SB(0, 1), b2 + hB, voffB); PG8_STAGE(PG8_SA(0, 0), a2, voffA);
;             PG8_WAIT_V(8); PG8_WAIT_L(0); PG8_BAR; PG8_MMA(1, 0, At, B0); PG8_MMA(1, 1, At, B1); PG8_BAR; PG8_SCHED;
;             PG8_LDB(B0, 1, 0); PG8_LDB(B1, 1, 1); PG8_SCHED; PG8_LDA(At, 1, 0); PG8_STAGE(PG8_SA(0, 1), a2 + hA, voffA);
;             PG8_WAIT_V(8); PG8_WAIT_L(0); PG8_BAR; PG8_MMA(0, 0, At, B0); PG8_MMA(0, 1, At, B1); PG8_BAR; PG8_SCHED;
;             PG8_LDA(At, 1, 1); PG8_STAGE(PG8_SB(1, 0), b3, voffB); PG8_STAGE(PG8_SB(1, 1), b3 + hB, voffB); PG8_STAGE(PG8_SA(1, 0), a3, voffA);
;             PG8_WAIT_V(8); PG8_WAIT_L(0); PG8_BAR; PG8_MMA(1, 0, At, B0); PG8_MMA(1, 1, At, B1); PG8_BAR; PG8_SCHED;
;         }
	s_add_i32 s61, 0, 0x18000
	s_add_i32 s94, 0, 0x1c000
	v_add_u32_e32 v140, s61, v219
	v_add_u32_e32 v156, s94, v219
	ds_read_b128 v[128:131], v140
	ds_read_b128 v[132:135], v140 offset:1024
	ds_read_b128 v[136:139], v140 offset:2048
	ds_read_b128 v[140:143], v140 offset:3072
	ds_read_b128 v[144:147], v156
	ds_read_b128 v[148:151], v156 offset:1024
	ds_read_b128 v[152:155], v156 offset:2048
	ds_read_b128 v[156:159], v156 offset:3072
	s_add_u32 s70, s8, 0x80000
	s_mov_b32 m0, s82
	ds_read_b128 v[160:163], v220 offset:32768
	ds_read_b128 v[164:167], v220 offset:33792
	ds_read_b128 v[168:171], v220 offset:34816
	ds_read_b128 v[172:175], v220 offset:35840
	ds_read_b128 v[176:179], v220 offset:36864
	ds_read_b128 v[180:183], v220 offset:37888
	ds_read_b128 v[184:187], v220 offset:38912
	ds_read_b128 v[188:191], v220 offset:39936
	s_addc_u32 s71, s9, 0
	s_nop 0
	global_load_lds_dwordx4 v217, s[70:71]
	s_mov_b32 m0, s83
	s_nop 0
	global_load_lds_dwordx4 v218, s[70:71]
	s_waitcnt vmcnt(8)
	s_waitcnt lgkmcnt(0)
	s_barrier
	s_setprio 1
	s_waitcnt lgkmcnt(0)
	v_mfma_f32_16x16x32_bf16 v[124:127], v[128:131], v[160:163], v[124:127]
	v_mfma_f32_16x16x32_bf16 v[116:119], v[136:139], v[160:163], v[116:119]
	v_mfma_f32_16x16x32_bf16 v[108:111], v[128:131], v[168:171], v[108:111]
	v_mfma_f32_16x16x32_bf16 v[104:107], v[136:139], v[168:171], v[104:107]
	v_mfma_f32_16x16x32_bf16 v[92:95], v[128:131], v[176:179], v[92:95]
	v_mfma_f32_16x16x32_bf16 v[88:91], v[136:139], v[176:179], v[88:91]
	v_mfma_f32_16x16x32_bf16 v[76:79], v[128:131], v[184:187], v[76:79]
	v_mfma_f32_16x16x32_bf16 v[72:75], v[136:139], v[184:187], v[72:75]
	v_mfma_f32_16x16x32_bf16 v[124:127], v[132:135], v[164:167], v[124:127]
	v_mfma_f32_16x16x32_bf16 v[116:119], v[140:143], v[164:167], v[116:119]
	v_mfma_f32_16x16x32_bf16 v[108:111], v[132:135], v[172:175], v[108:111]
	v_mfma_f32_16x16x32_bf16 v[104:107], v[140:143], v[172:175], v[104:107]
	v_mfma_f32_16x16x32_bf16 v[92:95], v[132:135], v[180:183], v[92:95]
	v_mfma_f32_16x16x32_bf16 v[88:91], v[140:143], v[180:183], v[88:91]
	v_mfma_f32_16x16x32_bf16 v[76:79], v[132:135], v[188:191], v[76:79]
	v_mfma_f32_16x16x32_bf16 v[72:75], v[140:143], v[188:191], v[72:75]
	v_mfma_f32_16x16x32_bf16 v[120:123], v[144:147], v[160:163], v[120:123]
	v_mfma_f32_16x16x32_bf16 v[112:115], v[152:155], v[160:163], v[112:115]
	v_mfma_f32_16x16x32_bf16 v[100:103], v[144:147], v[168:171], v[100:103]
	v_mfma_f32_16x16x32_bf16 v[96:99], v[152:155], v[168:171], v[96:99]
	v_mfma_f32_16x16x32_bf16 v[84:87], v[144:147], v[176:179], v[84:87]
	v_mfma_f32_16x16x32_bf16 v[80:83], v[152:155], v[176:179], v[80:83]
	v_mfma_f32_16x16x32_bf16 v[68:71], v[144:147], v[184:187], v[68:71]
	v_mfma_f32_16x16x32_bf16 v[64:67], v[152:155], v[184:187], v[64:67]
	v_mfma_f32_16x16x32_bf16 v[120:123], v[148:151], v[164:167], v[120:123]
	v_mfma_f32_16x16x32_bf16 v[112:115], v[156:159], v[164:167], v[112:115]
	v_mfma_f32_16x16x32_bf16 v[100:103], v[148:151], v[172:175], v[100:103]
	v_mfma_f32_16x16x32_bf16 v[96:99], v[156:159], v[172:175], v[96:99]
	v_mfma_f32_16x16x32_bf16 v[84:87], v[148:151], v[180:183], v[84:87]
	v_mfma_f32_16x16x32_bf16 v[80:83], v[156:159], v[180:183], v[80:83]
	v_mfma_f32_16x16x32_bf16 v[68:71], v[148:151], v[188:191], v[68:71]
	v_mfma_f32_16x16x32_bf16 v[64:67], v[156:159], v[188:191], v[64:67]
	s_setprio 0
	s_barrier
	ds_read_b128 v[160:163], v220 offset:49152
	ds_read_b128 v[164:167], v220 offset:50176
	ds_read_b128 v[168:171], v220 offset:51200
	ds_read_b128 v[172:175], v220 offset:52224
	ds_read_b128 v[176:179], v220 offset:53248
	ds_read_b128 v[180:183], v220 offset:54272
	ds_read_b128 v[184:187], v220 offset:55296
	ds_read_b128 v[188:191], v220 offset:56320
	s_add_i32 s61, s61, s79
	s_add_u32 s100, s10, s2
	s_addc_u32 s101, s11, s3
	s_mov_b32 m0, s61
	s_nop 0
	global_load_lds_dwordx4 v217, s[100:101]
	s_add_i32 m0, s61, 0x2000
	s_add_u32 s100, s10, s2
	s_addc_u32 s101, s11, s3
	s_add_u32 s10, s10, 0x80080
	global_load_lds_dwordx4 v218, s[100:101]
	s_addc_u32 s11, s11, 0
	s_add_i32 s61, s94, s79
	s_mov_b32 m0, s61
	s_nop 0
	global_load_lds_dwordx4 v217, s[10:11]
	s_add_i32 m0, s61, 0x2000
	s_nop 0
	global_load_lds_dwordx4 v218, s[10:11]
	s_mov_b32 m0, s87
	s_add_u32 s100, s8, s2
	s_addc_u32 s101, s9, s3
	global_load_lds_dwordx4 v217, s[100:101]
	s_mov_b32 m0, s88
	s_add_u32 s100, s8, s2
	s_addc_u32 s101, s9, s3
	global_load_lds_dwordx4 v218, s[100:101]
	s_waitcnt vmcnt(8)
	s_waitcnt lgkmcnt(0)
	s_barrier
	s_setprio 1
	s_waitcnt lgkmcnt(0)
	v_mfma_f32_16x16x32_bf16 v[60:63], v[128:131], v[160:163], v[60:63]
	v_mfma_f32_16x16x32_bf16 v[56:59], v[136:139], v[160:163], v[56:59]
	v_mfma_f32_16x16x32_bf16 v[44:47], v[128:131], v[168:171], v[44:47]
	v_mfma_f32_16x16x32_bf16 v[40:43], v[136:139], v[168:171], v[40:43]
	v_mfma_f32_16x16x32_bf16 v[28:31], v[128:131], v[176:179], v[28:31]
	v_mfma_f32_16x16x32_bf16 v[24:27], v[136:139], v[176:179], v[24:27]
	v_mfma_f32_16x16x32_bf16 v[12:15], v[128:131], v[184:187], v[12:15]
	v_mfma_f32_16x16x32_bf16 v[8:11], v[136:139], v[184:187], v[8:11]
	v_mfma_f32_16x16x32_bf16 v[60:63], v[132:135], v[164:167], v[60:63]
	v_mfma_f32_16x16x32_bf16 v[56:59], v[140:143], v[164:167], v[56:59]
	v_mfma_f32_16x16x32_bf16 v[44:47], v[132:135], v[172:175], v[44:47]
	v_mfma_f32_16x16x32_bf16 v[40:43], v[140:143], v[172:175], v[40:43]
	v_mfma_f32_16x16x32_bf16 v[28:31], v[132:135], v[180:183], v[28:31]
	v_mfma_f32_16x16x32_bf16 v[24:27], v[140:143], v[180:183], v[24:27]
	v_mfma_f32_16x16x32_bf16 v[12:15], v[132:135], v[188:191], v[12:15]
	v_mfma_f32_16x16x32_bf16 v[8:11], v[140:143], v[188:191], v[8:11]
	v_mfma_f32_16x16x32_bf16 v[52:55], v[144:147], v[160:163], v[52:55]
	v_mfma_f32_16x16x32_bf16 v[48:51], v[152:155], v[160:163], v[48:51]
	v_mfma_f32_16x16x32_bf16 v[36:39], v[144:147], v[168:171], v[36:39]
	v_mfma_f32_16x16x32_bf16 v[32:35], v[152:155], v[168:171], v[32:35]
	v_mfma_f32_16x16x32_bf16 v[20:23], v[144:147], v[176:179], v[20:23]
	v_mfma_f32_16x16x32_bf16 v[16:19], v[152:155], v[176:179], v[16:19]
	v_mfma_f32_16x16x32_bf16 v[4:7], v[144:147], v[184:187], v[4:7]
	v_mfma_f32_16x16x32_bf16 v[0:3], v[152:155], v[184:187], v[0:3]
	v_mfma_f32_16x16x32_bf16 v[52:55], v[148:151], v[164:167], v[52:55]
	v_mfma_f32_16x16x32_bf16 v[48:51], v[156:159], v[164:167], v[48:51]
	v_mfma_f32_16x16x32_bf16 v[36:39], v[148:151], v[172:175], v[36:39]
	v_mfma_f32_16x16x32_bf16 v[32:35], v[156:159], v[172:175], v[32:35]
	v_mfma_f32_16x16x32_bf16 v[20:23], v[148:151], v[180:183], v[20:23]
	v_mfma_f32_16x16x32_bf16 v[16:19], v[156:159], v[180:183], v[16:19]
	v_mfma_f32_16x16x32_bf16 v[4:7], v[148:151], v[188:191], v[4:7]
	v_mfma_f32_16x16x32_bf16 v[0:3], v[156:159], v[188:191], v[0:3]
	s_setprio 0
	s_barrier
	s_add_u32 s6, s6, 0x100
	s_addc_u32 s7, s7, 0
	s_add_u32 s15, s15, 0x100
	s_addc_u32 s33, s33, 0
	s_cmp_ge_i32 s59, s84
	s_mov_b32 s10, s59
	s_cbranch_scc0 .LBB0_160
	s_movk_i32 s12, 0xfff
	s_movk_i32 s94, 0x90
	s_mov_b32 s71, s37
	s_and_b64 vcc, exec, s[26:27]
	s_cbranch_vccnz .LBB0_163
	s_branch .LBB0_164

; #define PG8_STAGE(bufoff, gbase, voff) do { _Pragma("unroll") for (int _i = 0; _i < 2; ++_i) \
;         { unsigned vo_ = (voff) + _i * voff##_d; asm volatile("" : "+v"(vo_)); __builtin_amdgcn_global_load_lds((const unsigned*)((const char*)(gbase) + vo_), (PG8_LAS unsigned*)(lds + (bufoff) + ldsw + _i * 8192), 16, 0, 0); } } while (0)
; #define PG8_LDA(dst, b, h) do { _Pragma("unroll") for (int m = 0; m < 4; ++m) _Pragma("unroll") for (int k = 0; k < 2; ++k) dst[m][k] = *(const PG8_LAS bf16x8*)(lds + PG8_SA(b, h) + aoff + m * 2048 + k * 1024); } while (0)
; #define PG8_LDB(dst, b, h) do { _Pragma("unroll") for (int n = 0; n < 2; ++n) _Pragma("unroll") for (int k = 0; k < 2; ++k) dst[n][k] = *(const PG8_LAS bf16x8*)(lds + PG8_SB(b, h) + boff + n * 2048 + k * 1024); } while (0)
; template <class Epi, class Sched, bool ALIGN_EPI, bool F8 = false>
; __device__ __forceinline__ void gemm_phase(PG8_LAS unsigned char* lds, const Gemm g, const Sched& S, const Epi& E, const int wid) {
;     ...
;         for (int t = 0; t < nt; t += 2) {
;             const bool last = (t == nt - 2);
;             const char* a1 = cA + (size_t)(t + 1) * kstep;
;             const char* a2 = last ? nA : cA + (size_t)(t + 2) * kstep; const char* b2 = last ? nB : cB + (size_t)(t + 2) * kstep;
;             const char* a3 = a2 + kstep; const char* b3 = b2 + kstep;
;             PG8_LDB(B0, 0, 0); PG8_LDB(B1, 0, 1); PG8_SCHED; PG8_LDA(At, 0, 0); PG8_STAGE(PG8_SA(1, 1), a1 + hA, voffA);
;             PG8_WAIT_V(8); PG8_WAIT_L(0); PG8_BAR; PG8_MMA(0, 0, At, B0); PG8_MMA(0, 1, At, B1); PG8_BAR; PG8_SCHED;
;             PG8_LDA(At, 0, 1); PG8_STAGE(PG8_SB(0, 0), b2, voffB); PG8_STAGE(PG8_SB(0, 1), b2 + hB, voffB); PG8_STAGE(PG8_SA(0, 0), a2, voffA);
;             PG8_WAIT_V(8); PG8_WAIT_L(0); PG8_BAR; PG8_MMA(1, 0, At, B0); PG8_MMA(1, 1, At, B1); PG8_BAR; PG8_SCHED;
;             PG8_LDB(B0, 1, 0); PG8_LDB(B1, 1, 1); PG8_SCHED; PG8_LDA(At, 1, 0); PG8_STAGE(PG8_SA(0, 1), a2 + hA, voffA);
;             PG8_WAIT_V(8); PG8_WAIT_L(0); PG8_BAR; PG8_MMA(0, 0, At, B0); PG8_MMA(0, 1, At, B1); PG8_BAR; PG8_SCHED;
;             PG8_LDA(At, 1, 1); PG8_STAGE(PG8_SB(1, 0), b3, voffB); PG8_STAGE(PG8_SB(1, 1), b3 + hB, voffB); PG8_STAGE(PG8_SA(1, 0), a3, voffA);
;             PG8_WAIT_V(8); PG8_WAIT_L(0); PG8_BAR; PG8_MMA(1, 0, At, B0); PG8_MMA(1, 1, At, B1); PG8_BAR; PG8_SCHED;
;         }
.LBB0_1503:
	s_add_i32 s64, s34, 2
	s_add_u32 s36, s26, 0xfffc0080
	s_addc_u32 s35, s27, -1
	s_add_i32 s65, 0, 0x10000
	s_cmp_eq_u32 s54, s34
	s_cselect_b32 s35, s25, s35
	s_cselect_b32 s34, s58, s36
	s_cselect_b32 s37, s59, s63
	s_cselect_b32 s36, s60, s61
	s_add_i32 s68, 0, 0x14000
	v_add_u32_e32 v140, s65, v148
	v_add_u32_e32 v162, s68, v148
	ds_read_b128 v[120:123], v140
	ds_read_b128 v[124:127], v140 offset:1024
	ds_read_b128 v[136:139], v140 offset:2048
	ds_read_b128 v[140:143], v140 offset:3072
	ds_read_b128 v[150:153], v162
	ds_read_b128 v[154:157], v162 offset:1024
	ds_read_b128 v[158:161], v162 offset:2048
	ds_read_b128 v[162:165], v162 offset:3072
	ds_read_b128 v[166:169], v149
	ds_read_b128 v[170:173], v149 offset:1024
	ds_read_b128 v[174:177], v149 offset:2048
	ds_read_b128 v[178:181], v149 offset:3072
	ds_read_b128 v[182:185], v149 offset:4096
	ds_read_b128 v[186:189], v149 offset:5120
	ds_read_b128 v[190:193], v149 offset:6144
	ds_read_b128 v[194:197], v149 offset:7168
	s_add_i32 m0, s45, 0xc000
	s_nop 0
	global_load_lds_dwordx4 v144, s[26:27]
	s_add_i32 m0, s45, 0xe000
	s_nop 0
	global_load_lds_dwordx4 v147, s[26:27]
	s_waitcnt vmcnt(8)
	s_waitcnt lgkmcnt(0)
	s_barrier
	s_setprio 1
	s_waitcnt lgkmcnt(0)
	v_mfma_f32_16x16x32_bf16 v[128:131], v[120:123], v[166:169], v[128:131]
	v_mfma_f32_16x16x32_bf16 v[132:135], v[136:139], v[166:169], v[132:135]
	v_mfma_f32_16x16x32_bf16 v[116:119], v[120:123], v[174:177], v[116:119]
	v_mfma_f32_16x16x32_bf16 v[112:115], v[136:139], v[174:177], v[112:115]
	v_mfma_f32_16x16x32_bf16 v[108:111], v[120:123], v[182:185], v[108:111]
	v_mfma_f32_16x16x32_bf16 v[104:107], v[136:139], v[182:185], v[104:107]
	v_mfma_f32_16x16x32_bf16 v[100:103], v[120:123], v[190:193], v[100:103]
	v_mfma_f32_16x16x32_bf16 v[96:99], v[136:139], v[190:193], v[96:99]
	v_mfma_f32_16x16x32_bf16 v[128:131], v[124:127], v[170:173], v[128:131]
	v_mfma_f32_16x16x32_bf16 v[132:135], v[140:143], v[170:173], v[132:135]
	v_mfma_f32_16x16x32_bf16 v[116:119], v[124:127], v[178:181], v[116:119]
	v_mfma_f32_16x16x32_bf16 v[112:115], v[140:143], v[178:181], v[112:115]
	v_mfma_f32_16x16x32_bf16 v[108:111], v[124:127], v[186:189], v[108:111]
	v_mfma_f32_16x16x32_bf16 v[104:107], v[140:143], v[186:189], v[104:107]
	v_mfma_f32_16x16x32_bf16 v[100:103], v[124:127], v[194:197], v[100:103]
	v_mfma_f32_16x16x32_bf16 v[96:99], v[140:143], v[194:197], v[96:99]
	v_mfma_f32_16x16x32_bf16 v[60:63], v[150:153], v[166:169], v[60:63]
	v_mfma_f32_16x16x32_bf16 v[56:59], v[158:161], v[166:169], v[56:59]
	v_mfma_f32_16x16x32_bf16 v[52:55], v[150:153], v[174:177], v[52:55]
	v_mfma_f32_16x16x32_bf16 v[48:51], v[158:161], v[174:177], v[48:51]
	v_mfma_f32_16x16x32_bf16 v[44:47], v[150:153], v[182:185], v[44:47]
	v_mfma_f32_16x16x32_bf16 v[40:43], v[158:161], v[182:185], v[40:43]
	v_mfma_f32_16x16x32_bf16 v[36:39], v[150:153], v[190:193], v[36:39]
	v_mfma_f32_16x16x32_bf16 v[32:35], v[158:161], v[190:193], v[32:35]
	v_mfma_f32_16x16x32_bf16 v[60:63], v[154:157], v[170:173], v[60:63]
	v_mfma_f32_16x16x32_bf16 v[56:59], v[162:165], v[170:173], v[56:59]
	v_mfma_f32_16x16x32_bf16 v[52:55], v[154:157], v[178:181], v[52:55]
	v_mfma_f32_16x16x32_bf16 v[48:51], v[162:165], v[178:181], v[48:51]
	v_mfma_f32_16x16x32_bf16 v[44:47], v[154:157], v[186:189], v[44:47]
	v_mfma_f32_16x16x32_bf16 v[40:43], v[162:165], v[186:189], v[40:43]
	v_mfma_f32_16x16x32_bf16 v[36:39], v[154:157], v[194:197], v[36:39]
	v_mfma_f32_16x16x32_bf16 v[32:35], v[162:165], v[194:197], v[32:35]
	s_setprio 0
	s_barrier
	s_add_i32 s65, s65, s44
	ds_read_b128 v[166:169], v149 offset:16384
	ds_read_b128 v[170:173], v149 offset:17408
	ds_read_b128 v[174:177], v149 offset:18432
	ds_read_b128 v[178:181], v149 offset:19456
	ds_read_b128 v[182:185], v149 offset:20480
	ds_read_b128 v[186:189], v149 offset:21504
	ds_read_b128 v[190:193], v149 offset:22528
	ds_read_b128 v[194:197], v149 offset:23552
	s_mov_b32 m0, s65
	s_nop 0
	global_load_lds_dwordx4 v145, s[36:37]
	s_add_i32 m0, s65, 0x2000
	s_add_u32 s66, s36, 0x10000
	global_load_lds_dwordx4 v146, s[36:37]
	s_addc_u32 s67, s37, 0
	s_add_i32 s65, s68, s44
	s_mov_b32 m0, s65
	s_nop 0
	global_load_lds_dwordx4 v145, s[66:67]
	s_add_i32 m0, s65, 0x2000
	s_nop 0
	global_load_lds_dwordx4 v146, s[66:67]
	s_mov_b32 m0, s45
	s_nop 0
	global_load_lds_dwordx4 v144, s[34:35]
	s_mov_b32 m0, s46
	s_nop 0
	global_load_lds_dwordx4 v147, s[34:35]
	s_waitcnt vmcnt(8)
	s_waitcnt lgkmcnt(0)
	s_barrier
	s_setprio 1
	s_waitcnt lgkmcnt(0)
	v_mfma_f32_16x16x32_bf16 v[92:95], v[120:123], v[166:169], v[92:95]
	v_mfma_f32_16x16x32_bf16 v[88:91], v[136:139], v[166:169], v[88:91]
	v_mfma_f32_16x16x32_bf16 v[84:87], v[120:123], v[174:177], v[84:87]
	v_mfma_f32_16x16x32_bf16 v[80:83], v[136:139], v[174:177], v[80:83]
	v_mfma_f32_16x16x32_bf16 v[76:79], v[120:123], v[182:185], v[76:79]
	v_mfma_f32_16x16x32_bf16 v[72:75], v[136:139], v[182:185], v[72:75]
	v_mfma_f32_16x16x32_bf16 v[68:71], v[120:123], v[190:193], v[68:71]
	v_mfma_f32_16x16x32_bf16 v[64:67], v[136:139], v[190:193], v[64:67]
	v_mfma_f32_16x16x32_bf16 v[92:95], v[124:127], v[170:173], v[92:95]
	v_mfma_f32_16x16x32_bf16 v[88:91], v[140:143], v[170:173], v[88:91]
	v_mfma_f32_16x16x32_bf16 v[84:87], v[124:127], v[178:181], v[84:87]
	v_mfma_f32_16x16x32_bf16 v[80:83], v[140:143], v[178:181], v[80:83]
	v_mfma_f32_16x16x32_bf16 v[76:79], v[124:127], v[186:189], v[76:79]
	v_mfma_f32_16x16x32_bf16 v[72:75], v[140:143], v[186:189], v[72:75]
	v_mfma_f32_16x16x32_bf16 v[68:71], v[124:127], v[194:197], v[68:71]
	v_mfma_f32_16x16x32_bf16 v[64:67], v[140:143], v[194:197], v[64:67]
	v_mfma_f32_16x16x32_bf16 v[28:31], v[150:153], v[166:169], v[28:31]
	v_mfma_f32_16x16x32_bf16 v[24:27], v[158:161], v[166:169], v[24:27]
	v_mfma_f32_16x16x32_bf16 v[20:23], v[150:153], v[174:177], v[20:23]
	v_mfma_f32_16x16x32_bf16 v[16:19], v[158:161], v[174:177], v[16:19]
	v_mfma_f32_16x16x32_bf16 v[12:15], v[150:153], v[182:185], v[12:15]
	v_mfma_f32_16x16x32_bf16 v[8:11], v[158:161], v[182:185], v[8:11]
	v_mfma_f32_16x16x32_bf16 v[4:7], v[150:153], v[190:193], v[4:7]
	v_mfma_f32_16x16x32_bf16 v[0:3], v[158:161], v[190:193], v[0:3]
	v_mfma_f32_16x16x32_bf16 v[28:31], v[154:157], v[170:173], v[28:31]
	v_mfma_f32_16x16x32_bf16 v[24:27], v[162:165], v[170:173], v[24:27]
	v_mfma_f32_16x16x32_bf16 v[20:23], v[154:157], v[178:181], v[20:23]
	v_mfma_f32_16x16x32_bf16 v[16:19], v[162:165], v[178:181], v[16:19]
	v_mfma_f32_16x16x32_bf16 v[12:15], v[154:157], v[186:189], v[12:15]
	v_mfma_f32_16x16x32_bf16 v[8:11], v[162:165], v[186:189], v[8:11]
	v_mfma_f32_16x16x32_bf16 v[4:7], v[154:157], v[194:197], v[4:7]
	v_mfma_f32_16x16x32_bf16 v[0:3], v[162:165], v[194:197], v[0:3]
	s_setprio 0
	s_barrier
; #define PG8_STAGE(bufoff, gbase, voff) do { _Pragma("unroll") for (int _i = 0; _i < 2; ++_i) \
;         { unsigned vo_ = (voff) + _i * voff##_d; asm volatile("" : "+v"(vo_)); __builtin_amdgcn_global_load_lds((const unsigned*)((const char*)(gbase) + vo_), (PG8_LAS unsigned*)(lds + (bufoff) + ldsw + _i * 8192), 16, 0, 0); } } while (0)
; #define PG8_LDA(dst, b, h) do { _Pragma("unroll") for (int m = 0; m < 4; ++m) _Pragma("unroll") for (int k = 0; k < 2; ++k) dst[m][k] = *(const PG8_LAS bf16x8*)(lds + PG8_SA(b, h) + aoff + m * 2048 + k * 1024); } while (0)
; #define PG8_LDB(dst, b, h) do { _Pragma("unroll") for (int n = 0; n < 2; ++n) _Pragma("unroll") for (int k = 0; k < 2; ++k) dst[n][k] = *(const PG8_LAS bf16x8*)(lds + PG8_SB(b, h) + boff + n * 2048 + k * 1024); } while (0)
; template <class Epi, class Sched, bool ALIGN_EPI, bool F8 = false>
; __device__ __forceinline__ void gemm_phase(PG8_LAS unsigned char* lds, const Gemm g, const Sched& S, const Epi& E, const int wid) {
;     ...
;         for (int t = 0; t < nt; t += 2) {
;             const bool last = (t == nt - 2);
;             const char* a1 = cA + (size_t)(t + 1) * kstep;
;             const char* a2 = last ? nA : cA + (size_t)(t + 2) * kstep; const char* b2 = last ? nB : cB + (size_t)(t + 2) * kstep;
;             const char* a3 = a2 + kstep; const char* b3 = b2 + kstep;
;             PG8_LDB(B0, 0, 0); PG8_LDB(B1, 0, 1); PG8_SCHED; PG8_LDA(At, 0, 0); PG8_STAGE(PG8_SA(1, 1), a1 + hA, voffA);
;             PG8_WAIT_V(8); PG8_WAIT_L(0); PG8_BAR; PG8_MMA(0, 0, At, B0); PG8_MMA(0, 1, At, B1); PG8_BAR; PG8_SCHED;
;             PG8_LDA(At, 0, 1); PG8_STAGE(PG8_SB(0, 0), b2, voffB); PG8_STAGE(PG8_SB(0, 1), b2 + hB, voffB); PG8_STAGE(PG8_SA(0, 0), a2, voffA);
;             PG8_WAIT_V(8); PG8_WAIT_L(0); PG8_BAR; PG8_MMA(1, 0, At, B0); PG8_MMA(1, 1, At, B1); PG8_BAR; PG8_SCHED;
;             PG8_LDB(B0, 1, 0); PG8_LDB(B1, 1, 1); PG8_SCHED; PG8_LDA(At, 1, 0); PG8_STAGE(PG8_SA(0, 1), a2 + hA, voffA);
;             PG8_WAIT_V(8); PG8_WAIT_L(0); PG8_BAR; PG8_MMA(0, 0, At, B0); PG8_MMA(0, 1, At, B1); PG8_BAR; PG8_SCHED;
;             PG8_LDA(At, 1, 1); PG8_STAGE(PG8_SB(1, 0), b3, voffB); PG8_STAGE(PG8_SB(1, 1), b3 + hB, voffB); PG8_STAGE(PG8_SA(1, 0), a3, voffA);
;             PG8_WAIT_V(8); PG8_WAIT_L(0); PG8_BAR; PG8_MMA(1, 0, At, B0); PG8_MMA(1, 1, At, B1); PG8_BAR; PG8_SCHED;
;         }
	s_add_i32 s65, 0, 0x18000
	s_add_i32 s68, 0, 0x1c000
	v_add_u32_e32 v140, s65, v148
	v_add_u32_e32 v162, s68, v148
	ds_read_b128 v[120:123], v140
	ds_read_b128 v[124:127], v140 offset:1024
	ds_read_b128 v[136:139], v140 offset:2048
	ds_read_b128 v[140:143], v140 offset:3072
	ds_read_b128 v[150:153], v162
	ds_read_b128 v[154:157], v162 offset:1024
	ds_read_b128 v[158:161], v162 offset:2048
	ds_read_b128 v[162:165], v162 offset:3072
	s_add_u32 s66, s34, 0x40000
	s_mov_b32 m0, s47
	ds_read_b128 v[166:169], v149 offset:32768
	ds_read_b128 v[170:173], v149 offset:33792
	ds_read_b128 v[174:177], v149 offset:34816
	ds_read_b128 v[178:181], v149 offset:35840
	ds_read_b128 v[182:185], v149 offset:36864
	ds_read_b128 v[186:189], v149 offset:37888
	ds_read_b128 v[190:193], v149 offset:38912
	ds_read_b128 v[194:197], v149 offset:39936
	s_addc_u32 s67, s35, 0
	s_nop 0
	global_load_lds_dwordx4 v144, s[66:67]
	s_mov_b32 m0, s48
	s_nop 0
	global_load_lds_dwordx4 v147, s[66:67]
	s_waitcnt vmcnt(8)
	s_waitcnt lgkmcnt(0)
	s_barrier
	s_setprio 1
	s_waitcnt lgkmcnt(0)
	v_mfma_f32_16x16x32_bf16 v[128:131], v[120:123], v[166:169], v[128:131]
	v_mfma_f32_16x16x32_bf16 v[132:135], v[136:139], v[166:169], v[132:135]
	v_mfma_f32_16x16x32_bf16 v[116:119], v[120:123], v[174:177], v[116:119]
	v_mfma_f32_16x16x32_bf16 v[112:115], v[136:139], v[174:177], v[112:115]
	v_mfma_f32_16x16x32_bf16 v[108:111], v[120:123], v[182:185], v[108:111]
	v_mfma_f32_16x16x32_bf16 v[104:107], v[136:139], v[182:185], v[104:107]
	v_mfma_f32_16x16x32_bf16 v[100:103], v[120:123], v[190:193], v[100:103]
	v_mfma_f32_16x16x32_bf16 v[96:99], v[136:139], v[190:193], v[96:99]
	v_mfma_f32_16x16x32_bf16 v[128:131], v[124:127], v[170:173], v[128:131]
	v_mfma_f32_16x16x32_bf16 v[132:135], v[140:143], v[170:173], v[132:135]
	v_mfma_f32_16x16x32_bf16 v[116:119], v[124:127], v[178:181], v[116:119]
	v_mfma_f32_16x16x32_bf16 v[112:115], v[140:143], v[178:181], v[112:115]
	v_mfma_f32_16x16x32_bf16 v[108:111], v[124:127], v[186:189], v[108:111]
	v_mfma_f32_16x16x32_bf16 v[104:107], v[140:143], v[186:189], v[104:107]
	v_mfma_f32_16x16x32_bf16 v[100:103], v[124:127], v[194:197], v[100:103]
	v_mfma_f32_16x16x32_bf16 v[96:99], v[140:143], v[194:197], v[96:99]
	v_mfma_f32_16x16x32_bf16 v[60:63], v[150:153], v[166:169], v[60:63]
	v_mfma_f32_16x16x32_bf16 v[56:59], v[158:161], v[166:169], v[56:59]
	v_mfma_f32_16x16x32_bf16 v[52:55], v[150:153], v[174:177], v[52:55]
	v_mfma_f32_16x16x32_bf16 v[48:51], v[158:161], v[174:177], v[48:51]
	v_mfma_f32_16x16x32_bf16 v[44:47], v[150:153], v[182:185], v[44:47]
	v_mfma_f32_16x16x32_bf16 v[40:43], v[158:161], v[182:185], v[40:43]
	v_mfma_f32_16x16x32_bf16 v[36:39], v[150:153], v[190:193], v[36:39]
	v_mfma_f32_16x16x32_bf16 v[32:35], v[158:161], v[190:193], v[32:35]
	v_mfma_f32_16x16x32_bf16 v[60:63], v[154:157], v[170:173], v[60:63]
	v_mfma_f32_16x16x32_bf16 v[56:59], v[162:165], v[170:173], v[56:59]
	v_mfma_f32_16x16x32_bf16 v[52:55], v[154:157], v[178:181], v[52:55]
	v_mfma_f32_16x16x32_bf16 v[48:51], v[162:165], v[178:181], v[48:51]
	v_mfma_f32_16x16x32_bf16 v[44:47], v[154:157], v[186:189], v[44:47]
	v_mfma_f32_16x16x32_bf16 v[40:43], v[162:165], v[186:189], v[40:43]
	v_mfma_f32_16x16x32_bf16 v[36:39], v[154:157], v[194:197], v[36:39]
	v_mfma_f32_16x16x32_bf16 v[32:35], v[162:165], v[194:197], v[32:35]
	s_setprio 0
	s_barrier
	ds_read_b128 v[166:169], v149 offset:49152
	ds_read_b128 v[170:173], v149 offset:50176
	ds_read_b128 v[174:177], v149 offset:51200
	ds_read_b128 v[178:181], v149 offset:52224
	ds_read_b128 v[182:185], v149 offset:53248
	ds_read_b128 v[186:189], v149 offset:54272
	ds_read_b128 v[190:193], v149 offset:55296
	ds_read_b128 v[194:197], v149 offset:56320
	s_add_i32 s65, s65, s44
	s_add_u32 s100, s36, s2
	s_addc_u32 s101, s37, s3
	s_mov_b32 m0, s65
	s_nop 0
	global_load_lds_dwordx4 v145, s[100:101]
	s_add_i32 m0, s65, 0x2000
	s_add_u32 s100, s36, s2
	s_addc_u32 s101, s37, s3
	s_add_u32 s36, s36, 0x10080
	s_addc_u32 s37, s37, 0
	s_add_i32 s65, s68, s44
	global_load_lds_dwordx4 v146, s[100:101]
	s_mov_b32 m0, s65
	s_nop 0
	global_load_lds_dwordx4 v145, s[36:37]
	s_add_i32 m0, s65, 0x2000
	s_nop 0
	global_load_lds_dwordx4 v146, s[36:37]
	s_mov_b32 m0, s51
	s_add_u32 s100, s34, s2
	s_addc_u32 s101, s35, s3
	global_load_lds_dwordx4 v144, s[100:101]
	s_mov_b32 m0, s52
	s_add_u32 s100, s34, s2
	s_addc_u32 s101, s35, s3
	global_load_lds_dwordx4 v147, s[100:101]
	s_waitcnt vmcnt(8)
	s_waitcnt lgkmcnt(0)
	s_barrier
	s_setprio 1
	s_waitcnt lgkmcnt(0)
	v_mfma_f32_16x16x32_bf16 v[92:95], v[120:123], v[166:169], v[92:95]
	v_mfma_f32_16x16x32_bf16 v[88:91], v[136:139], v[166:169], v[88:91]
	v_mfma_f32_16x16x32_bf16 v[84:87], v[120:123], v[174:177], v[84:87]
	v_mfma_f32_16x16x32_bf16 v[80:83], v[136:139], v[174:177], v[80:83]
	v_mfma_f32_16x16x32_bf16 v[76:79], v[120:123], v[182:185], v[76:79]
	v_mfma_f32_16x16x32_bf16 v[72:75], v[136:139], v[182:185], v[72:75]
	v_mfma_f32_16x16x32_bf16 v[68:71], v[120:123], v[190:193], v[68:71]
	v_mfma_f32_16x16x32_bf16 v[64:67], v[136:139], v[190:193], v[64:67]
	v_mfma_f32_16x16x32_bf16 v[92:95], v[124:127], v[170:173], v[92:95]
	v_mfma_f32_16x16x32_bf16 v[88:91], v[140:143], v[170:173], v[88:91]
	v_mfma_f32_16x16x32_bf16 v[84:87], v[124:127], v[178:181], v[84:87]
	v_mfma_f32_16x16x32_bf16 v[80:83], v[140:143], v[178:181], v[80:83]
	v_mfma_f32_16x16x32_bf16 v[76:79], v[124:127], v[186:189], v[76:79]
	v_mfma_f32_16x16x32_bf16 v[72:75], v[140:143], v[186:189], v[72:75]
	v_mfma_f32_16x16x32_bf16 v[68:71], v[124:127], v[194:197], v[68:71]
	v_mfma_f32_16x16x32_bf16 v[64:67], v[140:143], v[194:197], v[64:67]
	v_mfma_f32_16x16x32_bf16 v[28:31], v[150:153], v[166:169], v[28:31]
	v_mfma_f32_16x16x32_bf16 v[24:27], v[158:161], v[166:169], v[24:27]
	v_mfma_f32_16x16x32_bf16 v[20:23], v[150:153], v[174:177], v[20:23]
	v_mfma_f32_16x16x32_bf16 v[16:19], v[158:161], v[174:177], v[16:19]
	v_mfma_f32_16x16x32_bf16 v[12:15], v[150:153], v[182:185], v[12:15]
	v_mfma_f32_16x16x32_bf16 v[8:11], v[158:161], v[182:185], v[8:11]
	v_mfma_f32_16x16x32_bf16 v[4:7], v[150:153], v[190:193], v[4:7]
	v_mfma_f32_16x16x32_bf16 v[0:3], v[158:161], v[190:193], v[0:3]
	v_mfma_f32_16x16x32_bf16 v[28:31], v[154:157], v[170:173], v[28:31]
	v_mfma_f32_16x16x32_bf16 v[24:27], v[162:165], v[170:173], v[24:27]
	v_mfma_f32_16x16x32_bf16 v[20:23], v[154:157], v[178:181], v[20:23]
	v_mfma_f32_16x16x32_bf16 v[16:19], v[162:165], v[178:181], v[16:19]
	v_mfma_f32_16x16x32_bf16 v[12:15], v[154:157], v[186:189], v[12:15]
	v_mfma_f32_16x16x32_bf16 v[8:11], v[162:165], v[186:189], v[8:11]
	v_mfma_f32_16x16x32_bf16 v[4:7], v[154:157], v[194:197], v[4:7]
	v_mfma_f32_16x16x32_bf16 v[0:3], v[162:165], v[194:197], v[0:3]
	s_setprio 0
	s_barrier
	s_add_u32 s26, s26, 0x100
	s_addc_u32 s27, s27, 0
	s_add_u32 s61, s61, 0x100
	s_addc_u32 s63, s63, 0
	s_cmp_ge_i32 s64, s53
	s_mov_b32 s34, s64
	s_cbranch_scc0 .LBB0_1503

; #define PG8_STAGE(bufoff, gbase, voff) do { _Pragma("unroll") for (int _i = 0; _i < 2; ++_i) \
;         { unsigned vo_ = (voff) + _i * voff##_d; asm volatile("" : "+v"(vo_)); __builtin_amdgcn_global_load_lds((const unsigned*)((const char*)(gbase) + vo_), (PG8_LAS unsigned*)(lds + (bufoff) + ldsw + _i * 8192), 16, 0, 0); } } while (0)
; #define PG8_LDA(dst, b, h) do { _Pragma("unroll") for (int m = 0; m < 4; ++m) _Pragma("unroll") for (int k = 0; k < 2; ++k) dst[m][k] = *(const PG8_LAS bf16x8*)(lds + PG8_SA(b, h) + aoff + m * 2048 + k * 1024); } while (0)
; #define PG8_LDB(dst, b, h) do { _Pragma("unroll") for (int n = 0; n < 2; ++n) _Pragma("unroll") for (int k = 0; k < 2; ++k) dst[n][k] = *(const PG8_LAS bf16x8*)(lds + PG8_SB(b, h) + boff + n * 2048 + k * 1024); } while (0)
; template <class Epi, class Sched, bool ALIGN_EPI, bool F8 = false>
; __device__ __forceinline__ void gemm_phase(PG8_LAS unsigned char* lds, const Gemm g, const Sched& S, const Epi& E, const int wid) {
;     ...
;         for (int t = 0; t < nt; t += 2) {
;             const bool last = (t == nt - 2);
;             const char* a1 = cA + (size_t)(t + 1) * kstep;
;             const char* a2 = last ? nA : cA + (size_t)(t + 2) * kstep; const char* b2 = last ? nB : cB + (size_t)(t + 2) * kstep;
;             const char* a3 = a2 + kstep; const char* b3 = b2 + kstep;
;             PG8_LDB(B0, 0, 0); PG8_LDB(B1, 0, 1); PG8_SCHED; PG8_LDA(At, 0, 0); PG8_STAGE(PG8_SA(1, 1), a1 + hA, voffA);
;             PG8_WAIT_V(8); PG8_WAIT_L(0); PG8_BAR; PG8_MMA(0, 0, At, B0); PG8_MMA(0, 1, At, B1); PG8_BAR; PG8_SCHED;
;             PG8_LDA(At, 0, 1); PG8_STAGE(PG8_SB(0, 0), b2, voffB); PG8_STAGE(PG8_SB(0, 1), b2 + hB, voffB); PG8_STAGE(PG8_SA(0, 0), a2, voffA);
;             PG8_WAIT_V(8); PG8_WAIT_L(0); PG8_BAR; PG8_MMA(1, 0, At, B0); PG8_MMA(1, 1, At, B1); PG8_BAR; PG8_SCHED;
;             PG8_LDB(B0, 1, 0); PG8_LDB(B1, 1, 1); PG8_SCHED; PG8_LDA(At, 1, 0); PG8_STAGE(PG8_SA(0, 1), a2 + hA, voffA);
;             PG8_WAIT_V(8); PG8_WAIT_L(0); PG8_BAR; PG8_MMA(0, 0, At, B0); PG8_MMA(0, 1, At, B1); PG8_BAR; PG8_SCHED;
;             PG8_LDA(At, 1, 1); PG8_STAGE(PG8_SB(1, 0), b3, voffB); PG8_STAGE(PG8_SB(1, 1), b3 + hB, voffB); PG8_STAGE(PG8_SA(1, 0), a3, voffA);
;             PG8_WAIT_V(8); PG8_WAIT_L(0); PG8_BAR; PG8_MMA(1, 0, At, B0); PG8_MMA(1, 1, At, B1); PG8_BAR; PG8_SCHED;
;         }
.LBB0_1770:
	s_add_i32 s59, s28, 2
	s_add_u32 s30, s26, 0xfffe0080
	s_addc_u32 s29, s27, -1
	s_add_i32 s60, 0, 0x10000
	s_cmp_eq_u32 s51, s28
	s_cselect_b32 s29, s13, s29
	s_cselect_b32 s28, s15, s30
	s_cselect_b32 s31, s55, s58
	s_cselect_b32 s30, s56, s57
	s_add_i32 s62, 0, 0x14000
	v_add_u32_e32 v140, s60, v186
	v_add_u32_e32 v156, s62, v186
	ds_read_b128 v[128:131], v140
	ds_read_b128 v[132:135], v140 offset:1024
	ds_read_b128 v[136:139], v140 offset:2048
	ds_read_b128 v[140:143], v140 offset:3072
	ds_read_b128 v[144:147], v156
	ds_read_b128 v[148:151], v156 offset:1024
	ds_read_b128 v[152:155], v156 offset:2048
	ds_read_b128 v[156:159], v156 offset:3072
	ds_read_b128 v[160:163], v187
	ds_read_b128 v[164:167], v187 offset:1024
	ds_read_b128 v[168:171], v187 offset:2048
	ds_read_b128 v[172:175], v187 offset:3072
	ds_read_b128 v[188:191], v187 offset:4096
	ds_read_b128 v[192:195], v187 offset:5120
	ds_read_b128 v[206:209], v187 offset:6144
	ds_read_b128 v[210:213], v187 offset:7168
	s_add_i32 m0, s40, 0xc000
	s_nop 0
	global_load_lds_dwordx4 v182, s[26:27]
	s_add_i32 m0, s40, 0xe000
	s_nop 0
	global_load_lds_dwordx4 v185, s[26:27]
	s_waitcnt vmcnt(8)
	s_waitcnt lgkmcnt(0)
	s_barrier
	s_setprio 1
	s_waitcnt lgkmcnt(0)
	v_mfma_f32_16x16x128_f8f6f4 v[124:127], v[128:135], v[160:167], v[124:127]
	v_mfma_f32_16x16x128_f8f6f4 v[120:123], v[136:143], v[160:167], v[120:123]
	v_mfma_f32_16x16x128_f8f6f4 v[116:119], v[128:135], v[168:175], v[116:119]
	v_mfma_f32_16x16x128_f8f6f4 v[112:115], v[136:143], v[168:175], v[112:115]
	v_mfma_f32_16x16x128_f8f6f4 v[104:107], v[128:135], v[188:195], v[104:107]
	v_mfma_f32_16x16x128_f8f6f4 v[176:179], v[136:143], v[188:195], v[96:99]
	v_mfma_f32_16x16x128_f8f6f4 v[196:199], v[128:135], v[206:213], v[88:91]
	v_mfma_f32_16x16x128_f8f6f4 v[202:205], v[136:143], v[206:213], v[80:83]
	v_mfma_f32_16x16x128_f8f6f4 v[108:111], v[144:151], v[160:167], v[108:111]
	v_mfma_f32_16x16x128_f8f6f4 v[100:103], v[152:159], v[160:167], v[100:103]
	v_mfma_f32_16x16x128_f8f6f4 v[60:63], v[152:159], v[206:213], v[60:63]
	v_mfma_f32_16x16x128_f8f6f4 v[160:163], v[144:151], v[168:175], v[92:95]
	v_mfma_f32_16x16x128_f8f6f4 v[164:167], v[152:159], v[168:175], v[84:87]
	v_mfma_f32_16x16x128_f8f6f4 v[168:171], v[144:151], v[188:195], v[76:79]
	v_mfma_f32_16x16x128_f8f6f4 v[172:175], v[152:159], v[188:195], v[72:75]
	v_mfma_f32_16x16x128_f8f6f4 v[188:191], v[144:151], v[206:213], v[68:71]
	s_setprio 0
	s_barrier
	s_add_i32 s60, s60, s39
	s_nop 2
	ds_read_b128 v[68:71], v187 offset:16384
	ds_read_b128 v[72:75], v187 offset:17408
	ds_read_b128 v[76:79], v187 offset:18432
	ds_read_b128 v[80:83], v187 offset:19456
	ds_read_b128 v[84:87], v187 offset:20480
	ds_read_b128 v[88:91], v187 offset:21504
	ds_read_b128 v[92:95], v187 offset:22528
	ds_read_b128 v[96:99], v187 offset:23552
	s_mov_b32 m0, s60
	s_nop 0
	global_load_lds_dwordx4 v183, s[30:31]
	s_add_i32 m0, s60, 0x2000
	s_add_u32 s60, s30, 0x20000
	global_load_lds_dwordx4 v184, s[30:31]
	s_addc_u32 s61, s31, 0
	s_add_i32 s62, s62, s39
	s_mov_b32 m0, s62
	s_nop 0
	global_load_lds_dwordx4 v183, s[60:61]
	s_add_i32 m0, s62, 0x2000
	s_nop 0
	global_load_lds_dwordx4 v184, s[60:61]
	s_mov_b32 m0, s40
	s_nop 0
	global_load_lds_dwordx4 v182, s[28:29]
	s_mov_b32 m0, s41
	s_nop 0
	global_load_lds_dwordx4 v185, s[28:29]
	s_waitcnt vmcnt(8)
	s_waitcnt lgkmcnt(0)
	s_barrier
	s_setprio 1
	s_waitcnt lgkmcnt(0)
	v_mfma_f32_16x16x128_f8f6f4 v[64:67], v[128:135], v[68:75], v[64:67]
	v_mfma_f32_16x16x128_f8f6f4 v[56:59], v[136:143], v[68:75], v[56:59]
	v_mfma_f32_16x16x128_f8f6f4 v[52:55], v[128:135], v[76:83], v[52:55]
	v_mfma_f32_16x16x128_f8f6f4 v[48:51], v[136:143], v[76:83], v[48:51]
	v_mfma_f32_16x16x128_f8f6f4 v[192:195], v[128:135], v[84:91], v[40:43]
	v_mfma_f32_16x16x128_f8f6f4 v[206:209], v[136:143], v[84:91], v[32:35]
	v_mfma_f32_16x16x128_f8f6f4 v[210:213], v[128:135], v[92:99], v[24:27]
	v_mfma_f32_16x16x128_f8f6f4 v[214:217], v[136:143], v[92:99], v[16:19]
	v_mfma_f32_16x16x128_f8f6f4 v[218:221], v[144:151], v[68:75], v[44:47]
	v_mfma_f32_16x16x128_f8f6f4 v[224:227], v[152:159], v[68:75], v[36:39]
	v_mfma_f32_16x16x128_f8f6f4 v[228:231], v[144:151], v[76:83], v[28:31]
	v_mfma_f32_16x16x128_f8f6f4 v[232:235], v[152:159], v[76:83], v[20:23]
	v_mfma_f32_16x16x128_f8f6f4 v[236:239], v[144:151], v[84:91], v[12:15]
	v_mfma_f32_16x16x128_f8f6f4 v[242:245], v[152:159], v[84:91], v[8:11]
	v_mfma_f32_16x16x128_f8f6f4 v[246:249], v[144:151], v[92:99], v[4:7]
	v_mfma_f32_16x16x128_f8f6f4 v[250:253], v[152:159], v[92:99], v[0:3]
	s_setprio 0
	s_barrier
	s_add_i32 s62, 0, 0x18000
	s_add_i32 s63, 0, 0x1c000
	v_add_u32_e32 v12, s62, v186
	v_add_u32_e32 v16, s63, v186
	s_nop 0
	ds_read_b128 v[0:3], v12
	ds_read_b128 v[4:7], v12 offset:1024
	ds_read_b128 v[8:11], v12 offset:2048
	ds_read_b128 v[12:15], v12 offset:3072
	ds_read_b128 v[128:131], v16
	ds_read_b128 v[132:135], v16 offset:1024
	ds_read_b128 v[136:139], v16 offset:2048
	ds_read_b128 v[140:143], v16 offset:3072
	s_add_u32 s60, s28, 0x20000
	s_mov_b32 m0, s42
	ds_read_b128 v[16:19], v187 offset:32768
	ds_read_b128 v[20:23], v187 offset:33792
	ds_read_b128 v[24:27], v187 offset:34816
	ds_read_b128 v[28:31], v187 offset:35840
	ds_read_b128 v[32:35], v187 offset:36864
	ds_read_b128 v[36:39], v187 offset:37888
	ds_read_b128 v[40:43], v187 offset:38912
	ds_read_b128 v[44:47], v187 offset:39936
	s_addc_u32 s61, s29, 0
	s_nop 0
	global_load_lds_dwordx4 v182, s[60:61]
	s_mov_b32 m0, s43
	s_nop 0
	global_load_lds_dwordx4 v185, s[60:61]
	s_waitcnt vmcnt(8)
	s_waitcnt lgkmcnt(0)
	s_barrier
; #define PG8_STAGE(bufoff, gbase, voff) do { _Pragma("unroll") for (int _i = 0; _i < 2; ++_i) \
;         { unsigned vo_ = (voff) + _i * voff##_d; asm volatile("" : "+v"(vo_)); __builtin_amdgcn_global_load_lds((const unsigned*)((const char*)(gbase) + vo_), (PG8_LAS unsigned*)(lds + (bufoff) + ldsw + _i * 8192), 16, 0, 0); } } while (0)
; #define PG8_LDA(dst, b, h) do { _Pragma("unroll") for (int m = 0; m < 4; ++m) _Pragma("unroll") for (int k = 0; k < 2; ++k) dst[m][k] = *(const PG8_LAS bf16x8*)(lds + PG8_SA(b, h) + aoff + m * 2048 + k * 1024); } while (0)
; #define PG8_LDB(dst, b, h) do { _Pragma("unroll") for (int n = 0; n < 2; ++n) _Pragma("unroll") for (int k = 0; k < 2; ++k) dst[n][k] = *(const PG8_LAS bf16x8*)(lds + PG8_SB(b, h) + boff + n * 2048 + k * 1024); } while (0)
; template <class Epi, class Sched, bool ALIGN_EPI, bool F8 = false>
; __device__ __forceinline__ void gemm_phase(PG8_LAS unsigned char* lds, const Gemm g, const Sched& S, const Epi& E, const int wid) {
;     ...
;         for (int t = 0; t < nt; t += 2) {
;             const bool last = (t == nt - 2);
;             const char* a1 = cA + (size_t)(t + 1) * kstep;
;             const char* a2 = last ? nA : cA + (size_t)(t + 2) * kstep; const char* b2 = last ? nB : cB + (size_t)(t + 2) * kstep;
;             const char* a3 = a2 + kstep; const char* b3 = b2 + kstep;
;             PG8_LDB(B0, 0, 0); PG8_LDB(B1, 0, 1); PG8_SCHED; PG8_LDA(At, 0, 0); PG8_STAGE(PG8_SA(1, 1), a1 + hA, voffA);
;             PG8_WAIT_V(8); PG8_WAIT_L(0); PG8_BAR; PG8_MMA(0, 0, At, B0); PG8_MMA(0, 1, At, B1); PG8_BAR; PG8_SCHED;
;             PG8_LDA(At, 0, 1); PG8_STAGE(PG8_SB(0, 0), b2, voffB); PG8_STAGE(PG8_SB(0, 1), b2 + hB, voffB); PG8_STAGE(PG8_SA(0, 0), a2, voffA);
;             PG8_WAIT_V(8); PG8_WAIT_L(0); PG8_BAR; PG8_MMA(1, 0, At, B0); PG8_MMA(1, 1, At, B1); PG8_BAR; PG8_SCHED;
;             PG8_LDB(B0, 1, 0); PG8_LDB(B1, 1, 1); PG8_SCHED; PG8_LDA(At, 1, 0); PG8_STAGE(PG8_SA(0, 1), a2 + hA, voffA);
;             PG8_WAIT_V(8); PG8_WAIT_L(0); PG8_BAR; PG8_MMA(0, 0, At, B0); PG8_MMA(0, 1, At, B1); PG8_BAR; PG8_SCHED;
;             PG8_LDA(At, 1, 1); PG8_STAGE(PG8_SB(1, 0), b3, voffB); PG8_STAGE(PG8_SB(1, 1), b3 + hB, voffB); PG8_STAGE(PG8_SA(1, 0), a3, voffA);
;             PG8_WAIT_V(8); PG8_WAIT_L(0); PG8_BAR; PG8_MMA(1, 0, At, B0); PG8_MMA(1, 1, At, B1); PG8_BAR; PG8_SCHED;
;         }
	s_setprio 1
	s_waitcnt lgkmcnt(0)
	v_mfma_f32_16x16x128_f8f6f4 v[124:127], v[0:7], v[16:23], v[124:127]
	v_mfma_f32_16x16x128_f8f6f4 v[120:123], v[8:15], v[16:23], v[120:123]
	v_mfma_f32_16x16x128_f8f6f4 v[116:119], v[0:7], v[24:31], v[116:119]
	v_mfma_f32_16x16x128_f8f6f4 v[112:115], v[8:15], v[24:31], v[112:115]
	v_mfma_f32_16x16x128_f8f6f4 v[104:107], v[0:7], v[32:39], v[104:107]
	v_mfma_f32_16x16x128_f8f6f4 v[96:99], v[8:15], v[32:39], v[176:179]
	v_mfma_f32_16x16x128_f8f6f4 v[88:91], v[0:7], v[40:47], v[196:199]
	v_mfma_f32_16x16x128_f8f6f4 v[80:83], v[8:15], v[40:47], v[202:205]
	v_mfma_f32_16x16x128_f8f6f4 v[108:111], v[128:135], v[16:23], v[108:111]
	v_mfma_f32_16x16x128_f8f6f4 v[100:103], v[136:143], v[16:23], v[100:103]
	v_mfma_f32_16x16x128_f8f6f4 v[92:95], v[128:135], v[24:31], v[160:163]
	v_mfma_f32_16x16x128_f8f6f4 v[84:87], v[136:143], v[24:31], v[164:167]
	v_mfma_f32_16x16x128_f8f6f4 v[76:79], v[128:135], v[32:39], v[168:171]
	v_mfma_f32_16x16x128_f8f6f4 v[72:75], v[136:143], v[32:39], v[172:175]
	v_mfma_f32_16x16x128_f8f6f4 v[68:71], v[128:135], v[40:47], v[188:191]
	v_mfma_f32_16x16x128_f8f6f4 v[60:63], v[136:143], v[40:47], v[60:63]
	s_setprio 0
	s_barrier
	ds_read_b128 v[144:147], v187 offset:49152
	ds_read_b128 v[148:151], v187 offset:50176
	ds_read_b128 v[152:155], v187 offset:51200
	ds_read_b128 v[156:159], v187 offset:52224
	ds_read_b128 v[160:163], v187 offset:53248
	ds_read_b128 v[164:167], v187 offset:54272
	ds_read_b128 v[168:171], v187 offset:55296
	ds_read_b128 v[172:175], v187 offset:56320
	s_add_i32 s60, s62, s39
	s_add_u32 s100, s30, s2
	s_addc_u32 s101, s31, s3
	s_mov_b32 m0, s60
	s_nop 0
	global_load_lds_dwordx4 v183, s[100:101]
	s_add_i32 m0, s60, 0x2000
	s_add_u32 s100, s30, s2
	s_addc_u32 s101, s31, s3
	s_add_u32 s30, s30, 0x20080
	global_load_lds_dwordx4 v184, s[100:101]
	s_addc_u32 s31, s31, 0
	s_add_i32 s60, s63, s39
	s_mov_b32 m0, s60
	s_nop 0
	global_load_lds_dwordx4 v183, s[30:31]
	s_add_i32 m0, s60, 0x2000
	s_nop 0
	global_load_lds_dwordx4 v184, s[30:31]
	s_mov_b32 m0, s49
	s_add_u32 s100, s28, s2
	s_addc_u32 s101, s29, s3
	global_load_lds_dwordx4 v182, s[100:101]
	s_mov_b32 m0, s50
	s_add_u32 s100, s28, s2
	s_addc_u32 s101, s29, s3
	global_load_lds_dwordx4 v185, s[100:101]
	s_waitcnt vmcnt(8)
	s_waitcnt lgkmcnt(0)
	s_barrier
	s_setprio 1
	s_waitcnt lgkmcnt(0)
	v_mfma_f32_16x16x128_f8f6f4 v[64:67], v[0:7], v[144:151], v[64:67]
	v_mfma_f32_16x16x128_f8f6f4 v[56:59], v[8:15], v[144:151], v[56:59]
	v_mfma_f32_16x16x128_f8f6f4 v[52:55], v[0:7], v[152:159], v[52:55]
	v_mfma_f32_16x16x128_f8f6f4 v[48:51], v[8:15], v[152:159], v[48:51]
	v_mfma_f32_16x16x128_f8f6f4 v[40:43], v[0:7], v[160:167], v[192:195]
	v_mfma_f32_16x16x128_f8f6f4 v[32:35], v[8:15], v[160:167], v[206:209]
	v_mfma_f32_16x16x128_f8f6f4 v[24:27], v[0:7], v[168:175], v[210:213]
	v_mfma_f32_16x16x128_f8f6f4 v[16:19], v[8:15], v[168:175], v[214:217]
	v_mfma_f32_16x16x128_f8f6f4 v[44:47], v[128:135], v[144:151], v[218:221]
	v_mfma_f32_16x16x128_f8f6f4 v[36:39], v[136:143], v[144:151], v[224:227]
	v_mfma_f32_16x16x128_f8f6f4 v[28:31], v[128:135], v[152:159], v[228:231]
	v_mfma_f32_16x16x128_f8f6f4 v[20:23], v[136:143], v[152:159], v[232:235]
	v_mfma_f32_16x16x128_f8f6f4 v[12:15], v[128:135], v[160:167], v[236:239]
	v_mfma_f32_16x16x128_f8f6f4 v[8:11], v[136:143], v[160:167], v[242:245]
	v_mfma_f32_16x16x128_f8f6f4 v[4:7], v[128:135], v[168:175], v[246:249]
	v_mfma_f32_16x16x128_f8f6f4 v[0:3], v[136:143], v[168:175], v[250:253]
	s_setprio 0
	s_barrier
	s_add_u32 s26, s26, 0x100
	s_addc_u32 s27, s27, 0
	s_add_u32 s57, s57, 0x100
	s_addc_u32 s58, s58, 0
	s_cmp_ge_i32 s59, s46
	s_mov_b32 s28, s59
	s_cbranch_scc0 .LBB0_1770
; __device__ __forceinline__ unsigned pk2(float lo, float hi) { typedef float f2_ __attribute__((ext_vector_type(2))); const bf16x2n_t b = __builtin_convertvector((f2_){lo, hi}, bf16x2n_t); return __builtin_bit_cast(unsigned, b); }
; __device__ __forceinline__ float gate_u8(unsigned w, int k) { return __builtin_fmaf((float)((w >> (8 * k)) & 0xffu), 1.0f / 255.0f, 0.5f / 255.0f); }
;     __device__ __forceinline__ void operator()(const f32x4 (&acc)[2][2][4][2], const pg8::Unit& u, int wr, int wc, int fr, int fq) const {
;     ...
;         for (int ai = 0; ai < 2; ++ai)
; #pragma unroll
;             for (int m = 0; m < 4; ++m) { const int r = row0 + ai * 128 + m * 16;
; #pragma unroll
;                 for (int bj = 0; bj < 2; ++bj) { const u32x2 g = gg[ai][m][bj];
;                     const f32x4 v0 = acc[ai][bj][m][0] * (1.0f / 32.0f), v1 = acc[ai][bj][m][1] * (1.0f / 32.0f);
;                     u32x4 w; w.x = pk2(v0[0] * gate_u8(g.x, 0), v0[1] * gate_u8(g.x, 1)); w.y = pk2(v0[2] * gate_u8(g.x, 2), v0[3] * gate_u8(g.x, 3)); w.z = pk2(v1[0] * gate_u8(g.y, 0), v1[1] * gate_u8(g.y, 1)); w.w = pk2(v1[2] * gate_u8(g.y, 2), v1[3] * gate_u8(g.y, 3));
	s_mov_b32 s26, 0x3d000000
	v_pk_mul_f32 v[148:149], v[126:127], s[26:27] op_sel_hi:[1,0]
	v_pk_mul_f32 v[156:157], v[124:125], s[26:27] op_sel_hi:[1,0]
	v_pk_mul_f32 v[152:153], v[122:123], s[26:27] op_sel_hi:[1,0]
	v_pk_mul_f32 v[154:155], v[120:121], s[26:27] op_sel_hi:[1,0]
	v_pk_mul_f32 v[126:127], v[110:111], s[26:27] op_sel_hi:[1,0]
	v_pk_mul_f32 v[130:131], v[108:109], s[26:27] op_sel_hi:[1,0]
	v_pk_mul_f32 v[124:125], v[102:103], s[26:27] op_sel_hi:[1,0]
	v_pk_mul_f32 v[128:129], v[100:101], s[26:27] op_sel_hi:[1,0]
	v_pk_mul_f32 v[118:119], v[118:119], s[26:27] op_sel_hi:[1,0]
	v_pk_mul_f32 v[122:123], v[116:117], s[26:27] op_sel_hi:[1,0]
	v_pk_mul_f32 v[110:111], v[114:115], s[26:27] op_sel_hi:[1,0]
	v_pk_mul_f32 v[116:117], v[112:113], s[26:27] op_sel_hi:[1,0]
	v_pk_mul_f32 v[112:113], v[94:95], s[26:27] op_sel_hi:[1,0]
	v_pk_mul_f32 v[120:121], v[92:93], s[26:27] op_sel_hi:[1,0]
	v_pk_mul_f32 v[108:109], v[86:87], s[26:27] op_sel_hi:[1,0]
	v_pk_mul_f32 v[114:115], v[84:85], s[26:27] op_sel_hi:[1,0]
	v_pk_mul_f32 v[100:101], v[106:107], s[26:27] op_sel_hi:[1,0]
	v_pk_mul_f32 v[106:107], v[104:105], s[26:27] op_sel_hi:[1,0]
	v_pk_mul_f32 v[94:95], v[98:99], s[26:27] op_sel_hi:[1,0]
	v_pk_mul_f32 v[102:103], v[96:97], s[26:27] op_sel_hi:[1,0]
	v_pk_mul_f32 v[96:97], v[78:79], s[26:27] op_sel_hi:[1,0]
	v_pk_mul_f32 v[104:105], v[76:77], s[26:27] op_sel_hi:[1,0]
	v_pk_mul_f32 v[92:93], v[74:75], s[26:27] op_sel_hi:[1,0]
	v_pk_mul_f32 v[98:99], v[72:73], s[26:27] op_sel_hi:[1,0]
	v_pk_mul_f32 v[84:85], v[90:91], s[26:27] op_sel_hi:[1,0]
	v_pk_mul_f32 v[90:91], v[88:89], s[26:27] op_sel_hi:[1,0]
	v_pk_mul_f32 v[78:79], v[82:83], s[26:27] op_sel_hi:[1,0]
	v_pk_mul_f32 v[86:87], v[80:81], s[26:27] op_sel_hi:[1,0]
	v_pk_mul_f32 v[80:81], v[70:71], s[26:27] op_sel_hi:[1,0]
	v_pk_mul_f32 v[88:89], v[68:69], s[26:27] op_sel_hi:[1,0]
	v_pk_mul_f32 v[76:77], v[62:63], s[26:27] op_sel_hi:[1,0]
	v_pk_mul_f32 v[82:83], v[60:61], s[26:27] op_sel_hi:[1,0]
	v_pk_mul_f32 v[68:69], v[66:67], s[26:27] op_sel_hi:[1,0]
	v_pk_mul_f32 v[74:75], v[64:65], s[26:27] op_sel_hi:[1,0]
	v_pk_mul_f32 v[62:63], v[58:59], s[26:27] op_sel_hi:[1,0]
	v_pk_mul_f32 v[70:71], v[56:57], s[26:27] op_sel_hi:[1,0]
	v_pk_mul_f32 v[64:65], v[46:47], s[26:27] op_sel_hi:[1,0]
	v_pk_mul_f32 v[72:73], v[44:45], s[26:27] op_sel_hi:[1,0]
	v_pk_mul_f32 v[60:61], v[38:39], s[26:27] op_sel_hi:[1,0]
	v_pk_mul_f32 v[66:67], v[36:37], s[26:27] op_sel_hi:[1,0]
	v_pk_mul_f32 v[54:55], v[54:55], s[26:27] op_sel_hi:[1,0]
	v_pk_mul_f32 v[58:59], v[52:53], s[26:27] op_sel_hi:[1,0]
	v_pk_mul_f32 v[46:47], v[50:51], s[26:27] op_sel_hi:[1,0]
	v_pk_mul_f32 v[52:53], v[48:49], s[26:27] op_sel_hi:[1,0]
	v_pk_mul_f32 v[48:49], v[30:31], s[26:27] op_sel_hi:[1,0]
	v_pk_mul_f32 v[56:57], v[28:29], s[26:27] op_sel_hi:[1,0]
	v_pk_mul_f32 v[44:45], v[22:23], s[26:27] op_sel_hi:[1,0]
	v_pk_mul_f32 v[50:51], v[20:21], s[26:27] op_sel_hi:[1,0]
	v_pk_mul_f32 v[36:37], v[42:43], s[26:27] op_sel_hi:[1,0]
	v_pk_mul_f32 v[40:41], v[40:41], s[26:27] op_sel_hi:[1,0]
	v_pk_mul_f32 v[28:29], v[34:35], s[26:27] op_sel_hi:[1,0]
	v_pk_mul_f32 v[34:35], v[32:33], s[26:27] op_sel_hi:[1,0]
	v_pk_mul_f32 v[30:31], v[14:15], s[26:27] op_sel_hi:[1,0]
	v_pk_mul_f32 v[38:39], v[12:13], s[26:27] op_sel_hi:[1,0]
	v_pk_mul_f32 v[22:23], v[10:11], s[26:27] op_sel_hi:[1,0]
	v_pk_mul_f32 v[32:33], v[8:9], s[26:27] op_sel_hi:[1,0]
	v_pk_mul_f32 v[12:13], v[26:27], s[26:27] op_sel_hi:[1,0]
	v_pk_mul_f32 v[20:21], v[24:25], s[26:27] op_sel_hi:[1,0]
	v_pk_mul_f32 v[8:9], v[18:19], s[26:27] op_sel_hi:[1,0]
	v_pk_mul_f32 v[14:15], v[16:17], s[26:27] op_sel_hi:[1,0]
	v_pk_mul_f32 v[6:7], v[6:7], s[26:27] op_sel_hi:[1,0]
	v_pk_mul_f32 v[16:17], v[4:5], s[26:27] op_sel_hi:[1,0]
	v_pk_mul_f32 v[4:5], v[2:3], s[26:27] op_sel_hi:[1,0]
	v_pk_mul_f32 v[10:11], v[0:1], s[26:27] op_sel_hi:[1,0]
	v_mov_b32_e32 v232, v181
	v_mov_b32_e32 v233, v223
	v_mov_b32_e32 v223, 0x260
	v_mov_b32_e32 v234, 0x1e000
	v_mov_b32_e32 v235, 0x7f800000
	v_mov_b32_e32 v236, 0x7fc00000
	v_mov_b32_e32 v237, 0x7fffff
	v_mov_b64_e32 v[238:239], 0x140
	v_mov_b64_e32 v[252:253], 0x13f
	v_mov_b32_e32 v198, 23

; #define PG8_STAGE(bufoff, gbase, voff) do { _Pragma("unroll") for (int _i = 0; _i < 2; ++_i) \
;         { unsigned vo_ = (voff) + _i * voff##_d; asm volatile("" : "+v"(vo_)); __builtin_amdgcn_global_load_lds((const unsigned*)((const char*)(gbase) + vo_), (PG8_LAS unsigned*)(lds + (bufoff) + ldsw + _i * 8192), 16, 0, 0); } } while (0)
; #define PG8_LDA(dst, b, h) do { _Pragma("unroll") for (int m = 0; m < 4; ++m) _Pragma("unroll") for (int k = 0; k < 2; ++k) dst[m][k] = *(const PG8_LAS bf16x8*)(lds + PG8_SA(b, h) + aoff + m * 2048 + k * 1024); } while (0)
; #define PG8_LDB(dst, b, h) do { _Pragma("unroll") for (int n = 0; n < 2; ++n) _Pragma("unroll") for (int k = 0; k < 2; ++k) dst[n][k] = *(const PG8_LAS bf16x8*)(lds + PG8_SB(b, h) + boff + n * 2048 + k * 1024); } while (0)
; template <class Epi, class Sched, bool ALIGN_EPI, bool F8 = false>
; __device__ __forceinline__ void gemm_phase(PG8_LAS unsigned char* lds, const Gemm g, const Sched& S, const Epi& E, const int wid) {
;     ...
;         for (int t = 0; t < nt; t += 2) {
;             const bool last = (t == nt - 2);
;             const char* a1 = cA + (size_t)(t + 1) * kstep;
;             const char* a2 = last ? nA : cA + (size_t)(t + 2) * kstep; const char* b2 = last ? nB : cB + (size_t)(t + 2) * kstep;
;             const char* a3 = a2 + kstep; const char* b3 = b2 + kstep;
;             PG8_LDB(B0, 0, 0); PG8_LDB(B1, 0, 1); PG8_SCHED; PG8_LDA(At, 0, 0); PG8_STAGE(PG8_SA(1, 1), a1 + hA, voffA);
;             PG8_WAIT_V(8); PG8_WAIT_L(0); PG8_BAR; PG8_MMA(0, 0, At, B0); PG8_MMA(0, 1, At, B1); PG8_BAR; PG8_SCHED;
;             PG8_LDA(At, 0, 1); PG8_STAGE(PG8_SB(0, 0), b2, voffB); PG8_STAGE(PG8_SB(0, 1), b2 + hB, voffB); PG8_STAGE(PG8_SA(0, 0), a2, voffA);
;             PG8_WAIT_V(8); PG8_WAIT_L(0); PG8_BAR; PG8_MMA(1, 0, At, B0); PG8_MMA(1, 1, At, B1); PG8_BAR; PG8_SCHED;
;             PG8_LDB(B0, 1, 0); PG8_LDB(B1, 1, 1); PG8_SCHED; PG8_LDA(At, 1, 0); PG8_STAGE(PG8_SA(0, 1), a2 + hA, voffA);
;             PG8_WAIT_V(8); PG8_WAIT_L(0); PG8_BAR; PG8_MMA(0, 0, At, B0); PG8_MMA(0, 1, At, B1); PG8_BAR; PG8_SCHED;
;             PG8_LDA(At, 1, 1); PG8_STAGE(PG8_SB(1, 0), b3, voffB); PG8_STAGE(PG8_SB(1, 1), b3 + hB, voffB); PG8_STAGE(PG8_SA(1, 0), a3, voffA);
;             PG8_WAIT_V(8); PG8_WAIT_L(0); PG8_BAR; PG8_MMA(1, 0, At, B0); PG8_MMA(1, 1, At, B1); PG8_BAR; PG8_SCHED;
;         }
.LBB0_1851:
	s_add_i32 s76, s48, 2
	s_add_u32 s50, s46, 0xfff80080
	s_addc_u32 s49, s47, -1
	s_add_i32 s77, 0, 0x10000
	s_cmp_eq_u32 s69, s48
	s_cselect_b32 s49, s23, s49
	s_cselect_b32 s48, s25, s50
	s_cselect_b32 s51, s72, s75
	s_cselect_b32 s50, s73, s74
	s_add_i32 s80, 0, 0x14000
	v_add_u32_e32 v140, s77, v243
	v_add_u32_e32 v156, s80, v243
	ds_read_b128 v[128:131], v140
	ds_read_b128 v[132:135], v140 offset:1024
	ds_read_b128 v[136:139], v140 offset:2048
	ds_read_b128 v[140:143], v140 offset:3072
	ds_read_b128 v[144:147], v156
	ds_read_b128 v[148:151], v156 offset:1024
	ds_read_b128 v[152:155], v156 offset:2048
	ds_read_b128 v[156:159], v156 offset:3072
	ds_read_b128 v[160:163], v244
	ds_read_b128 v[164:167], v244 offset:1024
	ds_read_b128 v[168:171], v244 offset:2048
	ds_read_b128 v[174:177], v244 offset:3072
	ds_read_b128 v[178:181], v244 offset:4096
	ds_read_b128 v[182:185], v244 offset:5120
	ds_read_b128 v[186:189], v244 offset:6144
	ds_read_b128 v[190:193], v244 offset:7168
	s_add_i32 m0, s60, 0xc000
	s_nop 0
	global_load_lds_dwordx4 v173, s[46:47]
	s_add_i32 m0, s60, 0xe000
	s_nop 0
	global_load_lds_dwordx4 v242, s[46:47]
	s_waitcnt vmcnt(8)
	s_waitcnt lgkmcnt(0)
	s_barrier
	s_setprio 1
	s_waitcnt lgkmcnt(0)
	v_mfma_f32_16x16x32_bf16 v[124:127], v[128:131], v[160:163], v[124:127]
	v_mfma_f32_16x16x32_bf16 v[120:123], v[136:139], v[160:163], v[120:123]
	v_mfma_f32_16x16x32_bf16 v[108:111], v[128:131], v[168:171], v[108:111]
	v_mfma_f32_16x16x32_bf16 v[104:107], v[136:139], v[168:171], v[104:107]
	v_mfma_f32_16x16x32_bf16 v[92:95], v[128:131], v[178:181], v[92:95]
	v_mfma_f32_16x16x32_bf16 v[88:91], v[136:139], v[178:181], v[88:91]
	v_mfma_f32_16x16x32_bf16 v[76:79], v[128:131], v[186:189], v[76:79]
	v_mfma_f32_16x16x32_bf16 v[72:75], v[136:139], v[186:189], v[72:75]
	v_mfma_f32_16x16x32_bf16 v[124:127], v[132:135], v[164:167], v[124:127]
	v_mfma_f32_16x16x32_bf16 v[120:123], v[140:143], v[164:167], v[120:123]
	v_mfma_f32_16x16x32_bf16 v[108:111], v[132:135], v[174:177], v[108:111]
	v_mfma_f32_16x16x32_bf16 v[104:107], v[140:143], v[174:177], v[104:107]
	v_mfma_f32_16x16x32_bf16 v[92:95], v[132:135], v[182:185], v[92:95]
	v_mfma_f32_16x16x32_bf16 v[88:91], v[140:143], v[182:185], v[88:91]
	v_mfma_f32_16x16x32_bf16 v[76:79], v[132:135], v[190:193], v[76:79]
	v_mfma_f32_16x16x32_bf16 v[72:75], v[140:143], v[190:193], v[72:75]
	v_mfma_f32_16x16x32_bf16 v[116:119], v[144:147], v[160:163], v[116:119]
	v_mfma_f32_16x16x32_bf16 v[112:115], v[152:155], v[160:163], v[112:115]
	v_mfma_f32_16x16x32_bf16 v[100:103], v[144:147], v[168:171], v[100:103]
	v_mfma_f32_16x16x32_bf16 v[96:99], v[152:155], v[168:171], v[96:99]
	v_mfma_f32_16x16x32_bf16 v[84:87], v[144:147], v[178:181], v[84:87]
	v_mfma_f32_16x16x32_bf16 v[80:83], v[152:155], v[178:181], v[80:83]
	v_mfma_f32_16x16x32_bf16 v[68:71], v[144:147], v[186:189], v[68:71]
	v_mfma_f32_16x16x32_bf16 v[64:67], v[152:155], v[186:189], v[64:67]
	v_mfma_f32_16x16x32_bf16 v[116:119], v[148:151], v[164:167], v[116:119]
	v_mfma_f32_16x16x32_bf16 v[112:115], v[156:159], v[164:167], v[112:115]
	v_mfma_f32_16x16x32_bf16 v[100:103], v[148:151], v[174:177], v[100:103]
	v_mfma_f32_16x16x32_bf16 v[96:99], v[156:159], v[174:177], v[96:99]
	v_mfma_f32_16x16x32_bf16 v[84:87], v[148:151], v[182:185], v[84:87]
	v_mfma_f32_16x16x32_bf16 v[80:83], v[156:159], v[182:185], v[80:83]
	v_mfma_f32_16x16x32_bf16 v[68:71], v[148:151], v[190:193], v[68:71]
	v_mfma_f32_16x16x32_bf16 v[64:67], v[156:159], v[190:193], v[64:67]
	s_setprio 0
	s_barrier
	s_add_i32 s77, s77, s58
	ds_read_b128 v[160:163], v244 offset:16384
	ds_read_b128 v[164:167], v244 offset:17408
	ds_read_b128 v[168:171], v244 offset:18432
	ds_read_b128 v[174:177], v244 offset:19456
	ds_read_b128 v[178:181], v244 offset:20480
	ds_read_b128 v[182:185], v244 offset:21504
	ds_read_b128 v[186:189], v244 offset:22528
	ds_read_b128 v[190:193], v244 offset:23552
	s_mov_b32 m0, s77
	s_nop 0
	global_load_lds_dwordx4 v173, s[50:51]
	s_add_i32 m0, s77, 0x2000
	s_add_u32 s78, s50, 0x80000
	global_load_lds_dwordx4 v242, s[50:51]
	s_addc_u32 s79, s51, 0
	s_add_i32 s77, s80, s58
	s_mov_b32 m0, s77
	s_nop 0
	global_load_lds_dwordx4 v173, s[78:79]
	s_add_i32 m0, s77, 0x2000
	s_nop 0
	global_load_lds_dwordx4 v242, s[78:79]
	s_mov_b32 m0, s60
	s_nop 0
	global_load_lds_dwordx4 v173, s[48:49]
	s_mov_b32 m0, s61
	s_nop 0
	global_load_lds_dwordx4 v242, s[48:49]
	s_waitcnt vmcnt(8)
	s_waitcnt lgkmcnt(0)
	s_barrier
	s_setprio 1
	s_waitcnt lgkmcnt(0)
	v_mfma_f32_16x16x32_bf16 v[60:63], v[128:131], v[160:163], v[60:63]
	v_mfma_f32_16x16x32_bf16 v[56:59], v[136:139], v[160:163], v[56:59]
	v_mfma_f32_16x16x32_bf16 v[44:47], v[128:131], v[168:171], v[44:47]
	v_mfma_f32_16x16x32_bf16 v[40:43], v[136:139], v[168:171], v[40:43]
	v_mfma_f32_16x16x32_bf16 v[28:31], v[128:131], v[178:181], v[28:31]
	v_mfma_f32_16x16x32_bf16 v[24:27], v[136:139], v[178:181], v[24:27]
	v_mfma_f32_16x16x32_bf16 v[12:15], v[128:131], v[186:189], v[12:15]
	v_mfma_f32_16x16x32_bf16 v[8:11], v[136:139], v[186:189], v[8:11]
	v_mfma_f32_16x16x32_bf16 v[60:63], v[132:135], v[164:167], v[60:63]
	v_mfma_f32_16x16x32_bf16 v[56:59], v[140:143], v[164:167], v[56:59]
	v_mfma_f32_16x16x32_bf16 v[44:47], v[132:135], v[174:177], v[44:47]
	v_mfma_f32_16x16x32_bf16 v[40:43], v[140:143], v[174:177], v[40:43]
	v_mfma_f32_16x16x32_bf16 v[28:31], v[132:135], v[182:185], v[28:31]
	v_mfma_f32_16x16x32_bf16 v[24:27], v[140:143], v[182:185], v[24:27]
	v_mfma_f32_16x16x32_bf16 v[12:15], v[132:135], v[190:193], v[12:15]
	v_mfma_f32_16x16x32_bf16 v[8:11], v[140:143], v[190:193], v[8:11]
	v_mfma_f32_16x16x32_bf16 v[52:55], v[144:147], v[160:163], v[52:55]
	v_mfma_f32_16x16x32_bf16 v[48:51], v[152:155], v[160:163], v[48:51]
	v_mfma_f32_16x16x32_bf16 v[36:39], v[144:147], v[168:171], v[36:39]
	v_mfma_f32_16x16x32_bf16 v[32:35], v[152:155], v[168:171], v[32:35]
	v_mfma_f32_16x16x32_bf16 v[20:23], v[144:147], v[178:181], v[20:23]
	v_mfma_f32_16x16x32_bf16 v[16:19], v[152:155], v[178:181], v[16:19]
	v_mfma_f32_16x16x32_bf16 v[4:7], v[144:147], v[186:189], v[4:7]
	v_mfma_f32_16x16x32_bf16 v[0:3], v[152:155], v[186:189], v[0:3]
	v_mfma_f32_16x16x32_bf16 v[52:55], v[148:151], v[164:167], v[52:55]
	v_mfma_f32_16x16x32_bf16 v[48:51], v[156:159], v[164:167], v[48:51]
	v_mfma_f32_16x16x32_bf16 v[36:39], v[148:151], v[174:177], v[36:39]
	v_mfma_f32_16x16x32_bf16 v[32:35], v[156:159], v[174:177], v[32:35]
	v_mfma_f32_16x16x32_bf16 v[20:23], v[148:151], v[182:185], v[20:23]
	v_mfma_f32_16x16x32_bf16 v[16:19], v[156:159], v[182:185], v[16:19]
	v_mfma_f32_16x16x32_bf16 v[4:7], v[148:151], v[190:193], v[4:7]
	v_mfma_f32_16x16x32_bf16 v[0:3], v[156:159], v[190:193], v[0:3]
	s_setprio 0
	s_barrier
; #define PG8_STAGE(bufoff, gbase, voff) do { _Pragma("unroll") for (int _i = 0; _i < 2; ++_i) \
;         { unsigned vo_ = (voff) + _i * voff##_d; asm volatile("" : "+v"(vo_)); __builtin_amdgcn_global_load_lds((const unsigned*)((const char*)(gbase) + vo_), (PG8_LAS unsigned*)(lds + (bufoff) + ldsw + _i * 8192), 16, 0, 0); } } while (0)
; #define PG8_LDA(dst, b, h) do { _Pragma("unroll") for (int m = 0; m < 4; ++m) _Pragma("unroll") for (int k = 0; k < 2; ++k) dst[m][k] = *(const PG8_LAS bf16x8*)(lds + PG8_SA(b, h) + aoff + m * 2048 + k * 1024); } while (0)
; #define PG8_LDB(dst, b, h) do { _Pragma("unroll") for (int n = 0; n < 2; ++n) _Pragma("unroll") for (int k = 0; k < 2; ++k) dst[n][k] = *(const PG8_LAS bf16x8*)(lds + PG8_SB(b, h) + boff + n * 2048 + k * 1024); } while (0)
; #define PG8_WAIT_V(n) asm volatile("s_waitcnt vmcnt(" #n ")" ::: "memory")
; #define PG8_WAIT_L(n) asm volatile("s_waitcnt lgkmcnt(" #n ")" ::: "memory")
; #define PG8_BAR __builtin_amdgcn_s_barrier()
; #define PG8_SCHED __builtin_amdgcn_sched_barrier(0)
; template <class Epi, class Sched, bool ALIGN_EPI, bool F8 = false>
; __device__ __forceinline__ void gemm_phase(PG8_LAS unsigned char* lds, const Gemm g, const Sched& S, const Epi& E, const int wid) {
;     ...
;             PG8_LDB(B0, 1, 0); PG8_LDB(B1, 1, 1); PG8_SCHED; PG8_LDA(At, 1, 0); PG8_STAGE(PG8_SA(0, 1), a2 + hA, voffA);
;             PG8_WAIT_V(8); PG8_WAIT_L(0); PG8_BAR; PG8_MMA(0, 0, At, B0); PG8_MMA(0, 1, At, B1); PG8_BAR; PG8_SCHED;
	s_add_i32 s77, 0, 0x18000
	s_add_i32 s80, 0, 0x1c000
	v_add_u32_e32 v140, s77, v243
	v_add_u32_e32 v156, s80, v243
	ds_read_b128 v[128:131], v140
	ds_read_b128 v[132:135], v140 offset:1024
	ds_read_b128 v[136:139], v140 offset:2048
	ds_read_b128 v[140:143], v140 offset:3072
	ds_read_b128 v[144:147], v156
	ds_read_b128 v[148:151], v156 offset:1024
	ds_read_b128 v[152:155], v156 offset:2048
	ds_read_b128 v[156:159], v156 offset:3072
	s_add_u32 s78, s48, 0x80000
	s_mov_b32 m0, s62
	ds_read_b128 v[160:163], v244 offset:32768
	ds_read_b128 v[164:167], v244 offset:33792
	ds_read_b128 v[168:171], v244 offset:34816
	ds_read_b128 v[174:177], v244 offset:35840
	ds_read_b128 v[178:181], v244 offset:36864
	ds_read_b128 v[182:185], v244 offset:37888
	ds_read_b128 v[186:189], v244 offset:38912
	ds_read_b128 v[190:193], v244 offset:39936
	s_addc_u32 s79, s49, 0
	s_nop 0
	global_load_lds_dwordx4 v173, s[78:79]
	s_mov_b32 m0, s63
	s_nop 0
	global_load_lds_dwordx4 v242, s[78:79]
	s_waitcnt vmcnt(8)
	s_waitcnt lgkmcnt(0)
	s_barrier
	s_setprio 1
	s_waitcnt lgkmcnt(0)
	v_mfma_f32_16x16x32_bf16 v[124:127], v[128:131], v[160:163], v[124:127]
	v_mfma_f32_16x16x32_bf16 v[120:123], v[136:139], v[160:163], v[120:123]
	v_mfma_f32_16x16x32_bf16 v[108:111], v[128:131], v[168:171], v[108:111]
	v_mfma_f32_16x16x32_bf16 v[104:107], v[136:139], v[168:171], v[104:107]
	v_mfma_f32_16x16x32_bf16 v[92:95], v[128:131], v[178:181], v[92:95]
	v_mfma_f32_16x16x32_bf16 v[88:91], v[136:139], v[178:181], v[88:91]
	v_mfma_f32_16x16x32_bf16 v[76:79], v[128:131], v[186:189], v[76:79]
	v_mfma_f32_16x16x32_bf16 v[72:75], v[136:139], v[186:189], v[72:75]
	v_mfma_f32_16x16x32_bf16 v[124:127], v[132:135], v[164:167], v[124:127]
	v_mfma_f32_16x16x32_bf16 v[120:123], v[140:143], v[164:167], v[120:123]
	v_mfma_f32_16x16x32_bf16 v[108:111], v[132:135], v[174:177], v[108:111]
	v_mfma_f32_16x16x32_bf16 v[104:107], v[140:143], v[174:177], v[104:107]
	v_mfma_f32_16x16x32_bf16 v[92:95], v[132:135], v[182:185], v[92:95]
	v_mfma_f32_16x16x32_bf16 v[88:91], v[140:143], v[182:185], v[88:91]
	v_mfma_f32_16x16x32_bf16 v[76:79], v[132:135], v[190:193], v[76:79]
	v_mfma_f32_16x16x32_bf16 v[72:75], v[140:143], v[190:193], v[72:75]
	v_mfma_f32_16x16x32_bf16 v[116:119], v[144:147], v[160:163], v[116:119]
	v_mfma_f32_16x16x32_bf16 v[112:115], v[152:155], v[160:163], v[112:115]
	v_mfma_f32_16x16x32_bf16 v[100:103], v[144:147], v[168:171], v[100:103]
	v_mfma_f32_16x16x32_bf16 v[96:99], v[152:155], v[168:171], v[96:99]
	v_mfma_f32_16x16x32_bf16 v[84:87], v[144:147], v[178:181], v[84:87]
	v_mfma_f32_16x16x32_bf16 v[80:83], v[152:155], v[178:181], v[80:83]
	v_mfma_f32_16x16x32_bf16 v[68:71], v[144:147], v[186:189], v[68:71]
	v_mfma_f32_16x16x32_bf16 v[64:67], v[152:155], v[186:189], v[64:67]
	v_mfma_f32_16x16x32_bf16 v[116:119], v[148:151], v[164:167], v[116:119]
	v_mfma_f32_16x16x32_bf16 v[112:115], v[156:159], v[164:167], v[112:115]
	v_mfma_f32_16x16x32_bf16 v[100:103], v[148:151], v[174:177], v[100:103]
	v_mfma_f32_16x16x32_bf16 v[96:99], v[156:159], v[174:177], v[96:99]
	v_mfma_f32_16x16x32_bf16 v[84:87], v[148:151], v[182:185], v[84:87]
	v_mfma_f32_16x16x32_bf16 v[80:83], v[156:159], v[182:185], v[80:83]
	v_mfma_f32_16x16x32_bf16 v[68:71], v[148:151], v[190:193], v[68:71]
	v_mfma_f32_16x16x32_bf16 v[64:67], v[156:159], v[190:193], v[64:67]
	s_setprio 0
	s_barrier
; #define PG8_STAGE(bufoff, gbase, voff) do { _Pragma("unroll") for (int _i = 0; _i < 2; ++_i) \
;         { unsigned vo_ = (voff) + _i * voff##_d; asm volatile("" : "+v"(vo_)); __builtin_amdgcn_global_load_lds((const unsigned*)((const char*)(gbase) + vo_), (PG8_LAS unsigned*)(lds + (bufoff) + ldsw + _i * 8192), 16, 0, 0); } } while (0)
; #define PG8_LDA(dst, b, h) do { _Pragma("unroll") for (int m = 0; m < 4; ++m) _Pragma("unroll") for (int k = 0; k < 2; ++k) dst[m][k] = *(const PG8_LAS bf16x8*)(lds + PG8_SA(b, h) + aoff + m * 2048 + k * 1024); } while (0)
; #define PG8_WAIT_V(n) asm volatile("s_waitcnt vmcnt(" #n ")" ::: "memory")
; #define PG8_WAIT_L(n) asm volatile("s_waitcnt lgkmcnt(" #n ")" ::: "memory")
; #define PG8_BAR __builtin_amdgcn_s_barrier()
; #define PG8_SCHED __builtin_amdgcn_sched_barrier(0)
; template <class Epi, class Sched, bool ALIGN_EPI, bool F8 = false>
; __device__ __forceinline__ void gemm_phase(PG8_LAS unsigned char* lds, const Gemm g, const Sched& S, const Epi& E, const int wid) {
;     ...
;             PG8_LDA(At, 1, 1); PG8_STAGE(PG8_SB(1, 0), b3, voffB); PG8_STAGE(PG8_SB(1, 1), b3 + hB, voffB); PG8_STAGE(PG8_SA(1, 0), a3, voffA);
;             PG8_WAIT_V(8); PG8_WAIT_L(0); PG8_BAR; PG8_MMA(1, 0, At, B0); PG8_MMA(1, 1, At, B1); PG8_BAR; PG8_SCHED;
	ds_read_b128 v[160:163], v244 offset:49152
	ds_read_b128 v[164:167], v244 offset:50176
	ds_read_b128 v[168:171], v244 offset:51200
	ds_read_b128 v[174:177], v244 offset:52224
	ds_read_b128 v[178:181], v244 offset:53248
	ds_read_b128 v[182:185], v244 offset:54272
	ds_read_b128 v[186:189], v244 offset:55296
	ds_read_b128 v[190:193], v244 offset:56320
	s_add_i32 s77, s77, s58
	s_add_u32 s100, s50, s2
	s_addc_u32 s101, s51, s3
	s_mov_b32 m0, s77
	s_nop 0
	global_load_lds_dwordx4 v173, s[100:101]
	s_add_i32 m0, s77, 0x2000
	s_add_u32 s100, s50, s2
	s_addc_u32 s101, s51, s3
	s_add_u32 s50, s50, 0x80080
	global_load_lds_dwordx4 v242, s[100:101]
	s_addc_u32 s51, s51, 0
	s_add_i32 s77, s80, s58
	s_mov_b32 m0, s77
	s_nop 0
	global_load_lds_dwordx4 v173, s[50:51]
	s_add_i32 m0, s77, 0x2000
	s_nop 0
	global_load_lds_dwordx4 v242, s[50:51]
	s_mov_b32 m0, s67
	s_add_u32 s100, s48, s2
	s_addc_u32 s101, s49, s3
	global_load_lds_dwordx4 v173, s[100:101]
	s_mov_b32 m0, s68
	s_add_u32 s100, s48, s2
	s_addc_u32 s101, s49, s3
	global_load_lds_dwordx4 v242, s[100:101]
	s_waitcnt vmcnt(8)
	s_waitcnt lgkmcnt(0)
	s_barrier
	s_setprio 1
	s_waitcnt lgkmcnt(0)
	v_mfma_f32_16x16x32_bf16 v[60:63], v[128:131], v[160:163], v[60:63]
	v_mfma_f32_16x16x32_bf16 v[56:59], v[136:139], v[160:163], v[56:59]
	v_mfma_f32_16x16x32_bf16 v[44:47], v[128:131], v[168:171], v[44:47]
	v_mfma_f32_16x16x32_bf16 v[40:43], v[136:139], v[168:171], v[40:43]
	v_mfma_f32_16x16x32_bf16 v[28:31], v[128:131], v[178:181], v[28:31]
	v_mfma_f32_16x16x32_bf16 v[24:27], v[136:139], v[178:181], v[24:27]
	v_mfma_f32_16x16x32_bf16 v[12:15], v[128:131], v[186:189], v[12:15]
	v_mfma_f32_16x16x32_bf16 v[8:11], v[136:139], v[186:189], v[8:11]
	v_mfma_f32_16x16x32_bf16 v[60:63], v[132:135], v[164:167], v[60:63]
	v_mfma_f32_16x16x32_bf16 v[56:59], v[140:143], v[164:167], v[56:59]
	v_mfma_f32_16x16x32_bf16 v[44:47], v[132:135], v[174:177], v[44:47]
	v_mfma_f32_16x16x32_bf16 v[40:43], v[140:143], v[174:177], v[40:43]
	v_mfma_f32_16x16x32_bf16 v[28:31], v[132:135], v[182:185], v[28:31]
	v_mfma_f32_16x16x32_bf16 v[24:27], v[140:143], v[182:185], v[24:27]
	v_mfma_f32_16x16x32_bf16 v[12:15], v[132:135], v[190:193], v[12:15]
	v_mfma_f32_16x16x32_bf16 v[8:11], v[140:143], v[190:193], v[8:11]
	v_mfma_f32_16x16x32_bf16 v[52:55], v[144:147], v[160:163], v[52:55]
	v_mfma_f32_16x16x32_bf16 v[48:51], v[152:155], v[160:163], v[48:51]
	v_mfma_f32_16x16x32_bf16 v[36:39], v[144:147], v[168:171], v[36:39]
	v_mfma_f32_16x16x32_bf16 v[32:35], v[152:155], v[168:171], v[32:35]
	v_mfma_f32_16x16x32_bf16 v[20:23], v[144:147], v[178:181], v[20:23]
	v_mfma_f32_16x16x32_bf16 v[16:19], v[152:155], v[178:181], v[16:19]
	v_mfma_f32_16x16x32_bf16 v[4:7], v[144:147], v[186:189], v[4:7]
	v_mfma_f32_16x16x32_bf16 v[0:3], v[152:155], v[186:189], v[0:3]
	v_mfma_f32_16x16x32_bf16 v[52:55], v[148:151], v[164:167], v[52:55]
	v_mfma_f32_16x16x32_bf16 v[48:51], v[156:159], v[164:167], v[48:51]
	v_mfma_f32_16x16x32_bf16 v[36:39], v[148:151], v[174:177], v[36:39]
	v_mfma_f32_16x16x32_bf16 v[32:35], v[156:159], v[174:177], v[32:35]
	v_mfma_f32_16x16x32_bf16 v[20:23], v[148:151], v[182:185], v[20:23]
	v_mfma_f32_16x16x32_bf16 v[16:19], v[156:159], v[182:185], v[16:19]
	v_mfma_f32_16x16x32_bf16 v[4:7], v[148:151], v[190:193], v[4:7]
	v_mfma_f32_16x16x32_bf16 v[0:3], v[156:159], v[190:193], v[0:3]
	s_setprio 0
	s_barrier
	s_add_u32 s46, s46, 0x100
	s_addc_u32 s47, s47, 0
	s_add_u32 s74, s74, 0x100
	s_addc_u32 s75, s75, 0
	s_cmp_ge_i32 s76, s64
	s_mov_b32 s48, s76
	s_cbranch_scc0 .LBB0_1851
	s_mov_b32 s76, 0x28000
	s_mov_b32 s75, 0x30000
	s_mov_b32 s72, 0x80000
	s_mov_b32 s73, 0x90000
	s_mov_b32 s74, 0xa0000
	s_mov_b32 s77, 0x3f400000
	s_mov_b32 s78, 0x3fa00000
	s_mov_b32 s79, 0x3fe00000
	s_mov_b32 s80, 0x40600000

; #define PG8_STAGE(bufoff, gbase, voff) do { _Pragma("unroll") for (int _i = 0; _i < 2; ++_i) \
;         { unsigned vo_ = (voff) + _i * voff##_d; asm volatile("" : "+v"(vo_)); __builtin_amdgcn_global_load_lds((const unsigned*)((const char*)(gbase) + vo_), (PG8_LAS unsigned*)(lds + (bufoff) + ldsw + _i * 8192), 16, 0, 0); } } while (0)
; #define PG8_LDA(dst, b, h) do { _Pragma("unroll") for (int m = 0; m < 4; ++m) _Pragma("unroll") for (int k = 0; k < 2; ++k) dst[m][k] = *(const PG8_LAS bf16x8*)(lds + PG8_SA(b, h) + aoff + m * 2048 + k * 1024); } while (0)
; #define PG8_LDB(dst, b, h) do { _Pragma("unroll") for (int n = 0; n < 2; ++n) _Pragma("unroll") for (int k = 0; k < 2; ++k) dst[n][k] = *(const PG8_LAS bf16x8*)(lds + PG8_SB(b, h) + boff + n * 2048 + k * 1024); } while (0)
; #define PG8_WAIT_V(n) asm volatile("s_waitcnt vmcnt(" #n ")" ::: "memory")
; #define PG8_WAIT_L(n) asm volatile("s_waitcnt lgkmcnt(" #n ")" ::: "memory")
; #define PG8_BAR __builtin_amdgcn_s_barrier()
; #define PG8_SCHED __builtin_amdgcn_sched_barrier(0)
; template <class Epi, class Sched, bool ALIGN_EPI, bool F8 = false>
; __device__ __forceinline__ void gemm_phase(PG8_LAS unsigned char* lds, const Gemm g, const Sched& S, const Epi& E, const int wid) {
;     ...
;             PG8_LDB(B0, 0, 0); PG8_LDB(B1, 0, 1); PG8_SCHED; PG8_LDA(At, 0, 0); PG8_STAGE(PG8_SA(1, 1), a1 + hA, voffA);
;             PG8_WAIT_V(8); PG8_WAIT_L(0); PG8_BAR; PG8_MMA(0, 0, At, B0); PG8_MMA(0, 1, At, B1); PG8_BAR; PG8_SCHED;
;             PG8_LDA(At, 0, 1); PG8_STAGE(PG8_SB(0, 0), b2, voffB); PG8_STAGE(PG8_SB(0, 1), b2 + hB, voffB); PG8_STAGE(PG8_SA(0, 0), a2, voffA);
;             PG8_WAIT_V(8); PG8_WAIT_L(0); PG8_BAR; PG8_MMA(1, 0, At, B0); PG8_MMA(1, 1, At, B1); PG8_BAR; PG8_SCHED;
.LBB0_1990:
	s_add_i32 s66, s28, 2
	s_add_u32 s30, s26, 0xfff80080
	s_addc_u32 s29, s27, -1
	s_add_i32 s67, 0, 0x10000
	s_cmp_eq_u32 s58, s28
	s_cselect_b32 s29, s15, s29
	s_cselect_b32 s28, s17, s30
	v_add_u32_e32 v135, s67, v133
	s_cselect_b32 s31, s62, s65
	s_cselect_b32 s30, s63, s64
	s_add_i32 s70, 0, 0x14000
	ds_read_b128 v[136:139], v135
	ds_read_b128 v[140:143], v135 offset:1024
	ds_read_b128 v[144:147], v135 offset:2048
	ds_read_b128 v[148:151], v135 offset:3072
	v_add_u32_e32 v135, s70, v133
	ds_read_b128 v[152:155], v135
	ds_read_b128 v[156:159], v135 offset:1024
	ds_read_b128 v[160:163], v135 offset:2048
	ds_read_b128 v[164:167], v135 offset:3072
	ds_read_b128 v[168:171], v134
	ds_read_b128 v[172:175], v134 offset:1024
	ds_read_b128 v[176:179], v134 offset:2048
	ds_read_b128 v[180:183], v134 offset:3072
	ds_read_b128 v[184:187], v134 offset:4096
	ds_read_b128 v[188:191], v134 offset:5120
	ds_read_b128 v[192:195], v134 offset:6144
	ds_read_b128 v[196:199], v134 offset:7168
	s_add_i32 m0, s13, 0xc000
	s_nop 0
	global_load_lds_dwordx4 v129, s[26:27]
	s_add_i32 m0, s13, 0xe000
	s_nop 0
	global_load_lds_dwordx4 v132, s[26:27]
	s_waitcnt vmcnt(8)
	s_waitcnt lgkmcnt(0)
	s_barrier
	s_setprio 1
	s_waitcnt lgkmcnt(0)
	v_mfma_f32_16x16x32_bf16 v[120:123], v[136:139], v[168:171], v[120:123]
	v_mfma_f32_16x16x32_bf16 v[124:127], v[144:147], v[168:171], v[124:127]
	v_mfma_f32_16x16x32_bf16 v[108:111], v[136:139], v[176:179], v[108:111]
	v_mfma_f32_16x16x32_bf16 v[104:107], v[144:147], v[176:179], v[104:107]
	v_mfma_f32_16x16x32_bf16 v[92:95], v[136:139], v[184:187], v[92:95]
	v_mfma_f32_16x16x32_bf16 v[88:91], v[144:147], v[184:187], v[88:91]
	v_mfma_f32_16x16x32_bf16 v[76:79], v[136:139], v[192:195], v[76:79]
	v_mfma_f32_16x16x32_bf16 v[72:75], v[144:147], v[192:195], v[72:75]
	v_mfma_f32_16x16x32_bf16 v[120:123], v[140:143], v[172:175], v[120:123]
	v_mfma_f32_16x16x32_bf16 v[124:127], v[148:151], v[172:175], v[124:127]
	v_mfma_f32_16x16x32_bf16 v[108:111], v[140:143], v[180:183], v[108:111]
	v_mfma_f32_16x16x32_bf16 v[104:107], v[148:151], v[180:183], v[104:107]
	v_mfma_f32_16x16x32_bf16 v[92:95], v[140:143], v[188:191], v[92:95]
	v_mfma_f32_16x16x32_bf16 v[88:91], v[148:151], v[188:191], v[88:91]
	v_mfma_f32_16x16x32_bf16 v[76:79], v[140:143], v[196:199], v[76:79]
	v_mfma_f32_16x16x32_bf16 v[72:75], v[148:151], v[196:199], v[72:75]
	v_mfma_f32_16x16x32_bf16 v[116:119], v[152:155], v[168:171], v[116:119]
	v_mfma_f32_16x16x32_bf16 v[112:115], v[160:163], v[168:171], v[112:115]
	v_mfma_f32_16x16x32_bf16 v[100:103], v[152:155], v[176:179], v[100:103]
	v_mfma_f32_16x16x32_bf16 v[96:99], v[160:163], v[176:179], v[96:99]
	v_mfma_f32_16x16x32_bf16 v[84:87], v[152:155], v[184:187], v[84:87]
	v_mfma_f32_16x16x32_bf16 v[80:83], v[160:163], v[184:187], v[80:83]
	v_mfma_f32_16x16x32_bf16 v[60:63], v[152:155], v[192:195], v[60:63]
	v_mfma_f32_16x16x32_bf16 v[56:59], v[160:163], v[192:195], v[56:59]
	v_mfma_f32_16x16x32_bf16 v[116:119], v[156:159], v[172:175], v[116:119]
	v_mfma_f32_16x16x32_bf16 v[112:115], v[164:167], v[172:175], v[112:115]
	v_mfma_f32_16x16x32_bf16 v[100:103], v[156:159], v[180:183], v[100:103]
	v_mfma_f32_16x16x32_bf16 v[96:99], v[164:167], v[180:183], v[96:99]
	v_mfma_f32_16x16x32_bf16 v[84:87], v[156:159], v[188:191], v[84:87]
	v_mfma_f32_16x16x32_bf16 v[80:83], v[164:167], v[188:191], v[80:83]
	v_mfma_f32_16x16x32_bf16 v[60:63], v[156:159], v[196:199], v[60:63]
	v_mfma_f32_16x16x32_bf16 v[56:59], v[164:167], v[196:199], v[56:59]
	s_setprio 0
	s_barrier
	s_add_i32 s67, s67, s47
	ds_read_b128 v[168:171], v134 offset:16384
	ds_read_b128 v[172:175], v134 offset:17408
	ds_read_b128 v[176:179], v134 offset:18432
	ds_read_b128 v[180:183], v134 offset:19456
	ds_read_b128 v[184:187], v134 offset:20480
	ds_read_b128 v[188:191], v134 offset:21504
	ds_read_b128 v[192:195], v134 offset:22528
	ds_read_b128 v[196:199], v134 offset:23552
	s_mov_b32 m0, s67
	s_nop 0
	global_load_lds_dwordx4 v130, s[30:31]
	s_add_i32 m0, s67, 0x2000
	s_add_u32 s68, s30, 0x80000
	global_load_lds_dwordx4 v131, s[30:31]
	s_addc_u32 s69, s31, 0
	s_add_i32 s67, s70, s47
	s_mov_b32 m0, s67
	s_nop 0
	global_load_lds_dwordx4 v130, s[68:69]
	s_add_i32 m0, s67, 0x2000
	s_nop 0
	global_load_lds_dwordx4 v131, s[68:69]
	s_mov_b32 m0, s13
	s_nop 0
	global_load_lds_dwordx4 v129, s[28:29]
	s_mov_b32 m0, s49
	s_nop 0
	global_load_lds_dwordx4 v132, s[28:29]
	s_waitcnt vmcnt(8)
	s_waitcnt lgkmcnt(0)
	s_barrier
	s_setprio 1
	s_waitcnt lgkmcnt(0)
	v_mfma_f32_16x16x32_bf16 v[68:71], v[136:139], v[168:171], v[68:71]
	v_mfma_f32_16x16x32_bf16 v[64:67], v[144:147], v[168:171], v[64:67]
	v_mfma_f32_16x16x32_bf16 v[44:47], v[136:139], v[176:179], v[44:47]
	v_mfma_f32_16x16x32_bf16 v[40:43], v[144:147], v[176:179], v[40:43]
	v_mfma_f32_16x16x32_bf16 v[28:31], v[136:139], v[184:187], v[28:31]
	v_mfma_f32_16x16x32_bf16 v[24:27], v[144:147], v[184:187], v[24:27]
	v_mfma_f32_16x16x32_bf16 v[12:15], v[136:139], v[192:195], v[12:15]
	v_mfma_f32_16x16x32_bf16 v[8:11], v[144:147], v[192:195], v[8:11]
	v_mfma_f32_16x16x32_bf16 v[68:71], v[140:143], v[172:175], v[68:71]
	v_mfma_f32_16x16x32_bf16 v[64:67], v[148:151], v[172:175], v[64:67]
	v_mfma_f32_16x16x32_bf16 v[44:47], v[140:143], v[180:183], v[44:47]
	v_mfma_f32_16x16x32_bf16 v[40:43], v[148:151], v[180:183], v[40:43]
	v_mfma_f32_16x16x32_bf16 v[28:31], v[140:143], v[188:191], v[28:31]
	v_mfma_f32_16x16x32_bf16 v[24:27], v[148:151], v[188:191], v[24:27]
	v_mfma_f32_16x16x32_bf16 v[12:15], v[140:143], v[196:199], v[12:15]
	v_mfma_f32_16x16x32_bf16 v[8:11], v[148:151], v[196:199], v[8:11]
	v_mfma_f32_16x16x32_bf16 v[52:55], v[152:155], v[168:171], v[52:55]
	v_mfma_f32_16x16x32_bf16 v[48:51], v[160:163], v[168:171], v[48:51]
	v_mfma_f32_16x16x32_bf16 v[36:39], v[152:155], v[176:179], v[36:39]
	v_mfma_f32_16x16x32_bf16 v[32:35], v[160:163], v[176:179], v[32:35]
	v_mfma_f32_16x16x32_bf16 v[20:23], v[152:155], v[184:187], v[20:23]
	v_mfma_f32_16x16x32_bf16 v[16:19], v[160:163], v[184:187], v[16:19]
	v_mfma_f32_16x16x32_bf16 v[4:7], v[152:155], v[192:195], v[4:7]
	v_mfma_f32_16x16x32_bf16 v[0:3], v[160:163], v[192:195], v[0:3]
	v_mfma_f32_16x16x32_bf16 v[52:55], v[156:159], v[172:175], v[52:55]
	v_mfma_f32_16x16x32_bf16 v[48:51], v[164:167], v[172:175], v[48:51]
	v_mfma_f32_16x16x32_bf16 v[36:39], v[156:159], v[180:183], v[36:39]
	v_mfma_f32_16x16x32_bf16 v[32:35], v[164:167], v[180:183], v[32:35]
	v_mfma_f32_16x16x32_bf16 v[20:23], v[156:159], v[188:191], v[20:23]
	v_mfma_f32_16x16x32_bf16 v[16:19], v[164:167], v[188:191], v[16:19]
	v_mfma_f32_16x16x32_bf16 v[4:7], v[156:159], v[196:199], v[4:7]
	v_mfma_f32_16x16x32_bf16 v[0:3], v[164:167], v[196:199], v[0:3]
	s_setprio 0
	s_barrier
; #define PG8_STAGE(bufoff, gbase, voff) do { _Pragma("unroll") for (int _i = 0; _i < 2; ++_i) \
;         { unsigned vo_ = (voff) + _i * voff##_d; asm volatile("" : "+v"(vo_)); __builtin_amdgcn_global_load_lds((const unsigned*)((const char*)(gbase) + vo_), (PG8_LAS unsigned*)(lds + (bufoff) + ldsw + _i * 8192), 16, 0, 0); } } while (0)
; #define PG8_LDA(dst, b, h) do { _Pragma("unroll") for (int m = 0; m < 4; ++m) _Pragma("unroll") for (int k = 0; k < 2; ++k) dst[m][k] = *(const PG8_LAS bf16x8*)(lds + PG8_SA(b, h) + aoff + m * 2048 + k * 1024); } while (0)
; #define PG8_LDB(dst, b, h) do { _Pragma("unroll") for (int n = 0; n < 2; ++n) _Pragma("unroll") for (int k = 0; k < 2; ++k) dst[n][k] = *(const PG8_LAS bf16x8*)(lds + PG8_SB(b, h) + boff + n * 2048 + k * 1024); } while (0)
; #define PG8_WAIT_V(n) asm volatile("s_waitcnt vmcnt(" #n ")" ::: "memory")
; #define PG8_WAIT_L(n) asm volatile("s_waitcnt lgkmcnt(" #n ")" ::: "memory")
; #define PG8_BAR __builtin_amdgcn_s_barrier()
; #define PG8_SCHED __builtin_amdgcn_sched_barrier(0)
; template <class Epi, class Sched, bool ALIGN_EPI, bool F8 = false>
; __device__ __forceinline__ void gemm_phase(PG8_LAS unsigned char* lds, const Gemm g, const Sched& S, const Epi& E, const int wid) {
;     ...
;             PG8_LDB(B0, 1, 0); PG8_LDB(B1, 1, 1); PG8_SCHED; PG8_LDA(At, 1, 0); PG8_STAGE(PG8_SA(0, 1), a2 + hA, voffA);
;             PG8_WAIT_V(8); PG8_WAIT_L(0); PG8_BAR; PG8_MMA(0, 0, At, B0); PG8_MMA(0, 1, At, B1); PG8_BAR; PG8_SCHED;
;             PG8_LDA(At, 1, 1); PG8_STAGE(PG8_SB(1, 0), b3, voffB); PG8_STAGE(PG8_SB(1, 1), b3 + hB, voffB); PG8_STAGE(PG8_SA(1, 0), a3, voffA);
;             PG8_WAIT_V(8); PG8_WAIT_L(0); PG8_BAR; PG8_MMA(1, 0, At, B0); PG8_MMA(1, 1, At, B1); PG8_BAR; PG8_SCHED;
	s_add_i32 s67, 0, 0x18000
	v_add_u32_e32 v135, s67, v133
	s_add_i32 s70, 0, 0x1c000
	ds_read_b128 v[136:139], v135
	ds_read_b128 v[140:143], v135 offset:1024
	ds_read_b128 v[144:147], v135 offset:2048
	ds_read_b128 v[148:151], v135 offset:3072
	v_add_u32_e32 v135, s70, v133
	ds_read_b128 v[152:155], v135
	ds_read_b128 v[156:159], v135 offset:1024
	ds_read_b128 v[160:163], v135 offset:2048
	ds_read_b128 v[164:167], v135 offset:3072
	s_add_u32 s68, s28, 0x80000
	s_mov_b32 m0, s50
	ds_read_b128 v[168:171], v134 offset:32768
	ds_read_b128 v[172:175], v134 offset:33792
	ds_read_b128 v[176:179], v134 offset:34816
	ds_read_b128 v[180:183], v134 offset:35840
	ds_read_b128 v[184:187], v134 offset:36864
	ds_read_b128 v[188:191], v134 offset:37888
	ds_read_b128 v[192:195], v134 offset:38912
	ds_read_b128 v[196:199], v134 offset:39936
	s_addc_u32 s69, s29, 0
	s_nop 0
	global_load_lds_dwordx4 v129, s[68:69]
	s_mov_b32 m0, s51
	s_nop 0
	global_load_lds_dwordx4 v132, s[68:69]
	s_waitcnt vmcnt(8)
	s_waitcnt lgkmcnt(0)
	s_barrier
	s_setprio 1
	s_waitcnt lgkmcnt(0)
	v_mfma_f32_16x16x32_bf16 v[120:123], v[136:139], v[168:171], v[120:123]
	v_mfma_f32_16x16x32_bf16 v[124:127], v[144:147], v[168:171], v[124:127]
	v_mfma_f32_16x16x32_bf16 v[108:111], v[136:139], v[176:179], v[108:111]
	v_mfma_f32_16x16x32_bf16 v[104:107], v[144:147], v[176:179], v[104:107]
	v_mfma_f32_16x16x32_bf16 v[92:95], v[136:139], v[184:187], v[92:95]
	v_mfma_f32_16x16x32_bf16 v[88:91], v[144:147], v[184:187], v[88:91]
	v_mfma_f32_16x16x32_bf16 v[76:79], v[136:139], v[192:195], v[76:79]
	v_mfma_f32_16x16x32_bf16 v[72:75], v[144:147], v[192:195], v[72:75]
	v_mfma_f32_16x16x32_bf16 v[120:123], v[140:143], v[172:175], v[120:123]
	v_mfma_f32_16x16x32_bf16 v[124:127], v[148:151], v[172:175], v[124:127]
	v_mfma_f32_16x16x32_bf16 v[108:111], v[140:143], v[180:183], v[108:111]
	v_mfma_f32_16x16x32_bf16 v[104:107], v[148:151], v[180:183], v[104:107]
	v_mfma_f32_16x16x32_bf16 v[92:95], v[140:143], v[188:191], v[92:95]
	v_mfma_f32_16x16x32_bf16 v[88:91], v[148:151], v[188:191], v[88:91]
	v_mfma_f32_16x16x32_bf16 v[76:79], v[140:143], v[196:199], v[76:79]
	v_mfma_f32_16x16x32_bf16 v[72:75], v[148:151], v[196:199], v[72:75]
	v_mfma_f32_16x16x32_bf16 v[116:119], v[152:155], v[168:171], v[116:119]
	v_mfma_f32_16x16x32_bf16 v[112:115], v[160:163], v[168:171], v[112:115]
	v_mfma_f32_16x16x32_bf16 v[100:103], v[152:155], v[176:179], v[100:103]
	v_mfma_f32_16x16x32_bf16 v[96:99], v[160:163], v[176:179], v[96:99]
	v_mfma_f32_16x16x32_bf16 v[84:87], v[152:155], v[184:187], v[84:87]
	v_mfma_f32_16x16x32_bf16 v[80:83], v[160:163], v[184:187], v[80:83]
	v_mfma_f32_16x16x32_bf16 v[60:63], v[152:155], v[192:195], v[60:63]
	v_mfma_f32_16x16x32_bf16 v[56:59], v[160:163], v[192:195], v[56:59]
	v_mfma_f32_16x16x32_bf16 v[116:119], v[156:159], v[172:175], v[116:119]
	v_mfma_f32_16x16x32_bf16 v[112:115], v[164:167], v[172:175], v[112:115]
	v_mfma_f32_16x16x32_bf16 v[100:103], v[156:159], v[180:183], v[100:103]
	v_mfma_f32_16x16x32_bf16 v[96:99], v[164:167], v[180:183], v[96:99]
	v_mfma_f32_16x16x32_bf16 v[84:87], v[156:159], v[188:191], v[84:87]
	v_mfma_f32_16x16x32_bf16 v[80:83], v[164:167], v[188:191], v[80:83]
	v_mfma_f32_16x16x32_bf16 v[60:63], v[156:159], v[196:199], v[60:63]
	v_mfma_f32_16x16x32_bf16 v[56:59], v[164:167], v[196:199], v[56:59]
	s_setprio 0
	s_barrier
	ds_read_b128 v[168:171], v134 offset:49152
	ds_read_b128 v[172:175], v134 offset:50176
	ds_read_b128 v[176:179], v134 offset:51200
	ds_read_b128 v[180:183], v134 offset:52224
	ds_read_b128 v[184:187], v134 offset:53248
	ds_read_b128 v[188:191], v134 offset:54272
	ds_read_b128 v[192:195], v134 offset:55296
	ds_read_b128 v[196:199], v134 offset:56320
	s_add_i32 s67, s67, s47
	s_add_u32 s100, s30, s2
	s_addc_u32 s101, s31, s3
	s_mov_b32 m0, s67
	s_nop 0
	global_load_lds_dwordx4 v130, s[100:101]
	s_add_i32 m0, s67, 0x2000
	s_add_u32 s100, s30, s2
	s_addc_u32 s101, s31, s3
	s_add_u32 s30, s30, 0x80080
	s_addc_u32 s31, s31, 0
	s_add_i32 s67, s70, s47
	global_load_lds_dwordx4 v131, s[100:101]
	s_mov_b32 m0, s67
	s_nop 0
	global_load_lds_dwordx4 v130, s[30:31]
	s_add_i32 m0, s67, 0x2000
	s_nop 0
	global_load_lds_dwordx4 v131, s[30:31]
	s_mov_b32 m0, s56
	s_add_u32 s100, s28, s2
	s_addc_u32 s101, s29, s3
	global_load_lds_dwordx4 v129, s[100:101]
	s_mov_b32 m0, s57
	s_add_u32 s100, s28, s2
	s_addc_u32 s101, s29, s3
	global_load_lds_dwordx4 v132, s[100:101]
	s_waitcnt vmcnt(8)
	s_waitcnt lgkmcnt(0)
	s_barrier
	s_setprio 1
	s_waitcnt lgkmcnt(0)
	v_mfma_f32_16x16x32_bf16 v[68:71], v[136:139], v[168:171], v[68:71]
	v_mfma_f32_16x16x32_bf16 v[64:67], v[144:147], v[168:171], v[64:67]
	v_mfma_f32_16x16x32_bf16 v[44:47], v[136:139], v[176:179], v[44:47]
	v_mfma_f32_16x16x32_bf16 v[40:43], v[144:147], v[176:179], v[40:43]
	v_mfma_f32_16x16x32_bf16 v[28:31], v[136:139], v[184:187], v[28:31]
	v_mfma_f32_16x16x32_bf16 v[24:27], v[144:147], v[184:187], v[24:27]
	v_mfma_f32_16x16x32_bf16 v[12:15], v[136:139], v[192:195], v[12:15]
	v_mfma_f32_16x16x32_bf16 v[8:11], v[144:147], v[192:195], v[8:11]
	v_mfma_f32_16x16x32_bf16 v[68:71], v[140:143], v[172:175], v[68:71]
	v_mfma_f32_16x16x32_bf16 v[64:67], v[148:151], v[172:175], v[64:67]
	v_mfma_f32_16x16x32_bf16 v[44:47], v[140:143], v[180:183], v[44:47]
	v_mfma_f32_16x16x32_bf16 v[40:43], v[148:151], v[180:183], v[40:43]
	v_mfma_f32_16x16x32_bf16 v[28:31], v[140:143], v[188:191], v[28:31]
	v_mfma_f32_16x16x32_bf16 v[24:27], v[148:151], v[188:191], v[24:27]
	v_mfma_f32_16x16x32_bf16 v[12:15], v[140:143], v[196:199], v[12:15]
	v_mfma_f32_16x16x32_bf16 v[8:11], v[148:151], v[196:199], v[8:11]
	v_mfma_f32_16x16x32_bf16 v[52:55], v[152:155], v[168:171], v[52:55]
	v_mfma_f32_16x16x32_bf16 v[48:51], v[160:163], v[168:171], v[48:51]
	v_mfma_f32_16x16x32_bf16 v[36:39], v[152:155], v[176:179], v[36:39]
	v_mfma_f32_16x16x32_bf16 v[32:35], v[160:163], v[176:179], v[32:35]
	v_mfma_f32_16x16x32_bf16 v[20:23], v[152:155], v[184:187], v[20:23]
	v_mfma_f32_16x16x32_bf16 v[16:19], v[160:163], v[184:187], v[16:19]
	v_mfma_f32_16x16x32_bf16 v[4:7], v[152:155], v[192:195], v[4:7]
	v_mfma_f32_16x16x32_bf16 v[0:3], v[160:163], v[192:195], v[0:3]
	v_mfma_f32_16x16x32_bf16 v[52:55], v[156:159], v[172:175], v[52:55]
	v_mfma_f32_16x16x32_bf16 v[48:51], v[164:167], v[172:175], v[48:51]
	v_mfma_f32_16x16x32_bf16 v[36:39], v[156:159], v[180:183], v[36:39]
	v_mfma_f32_16x16x32_bf16 v[32:35], v[164:167], v[180:183], v[32:35]
	v_mfma_f32_16x16x32_bf16 v[20:23], v[156:159], v[188:191], v[20:23]
	v_mfma_f32_16x16x32_bf16 v[16:19], v[164:167], v[188:191], v[16:19]
	v_mfma_f32_16x16x32_bf16 v[4:7], v[156:159], v[196:199], v[4:7]
	v_mfma_f32_16x16x32_bf16 v[0:3], v[164:167], v[196:199], v[0:3]
	s_setprio 0
	s_barrier
	s_add_u32 s26, s26, 0x100
	s_addc_u32 s27, s27, 0
	s_add_u32 s64, s64, 0x100
	s_addc_u32 s65, s65, 0
	s_cmp_ge_i32 s66, s52
	s_mov_b32 s28, s66
	s_cbranch_scc0 .LBB0_1990
	v_mov_b32_e32 v198, v204
